# 3/5 DMA rebalance + snake MFMA order + software-pipelined LDS reads in mixer MFMA sections
# speedup vs baseline: 1.0093x; 1.0017x over previous
; #define PG8_STAGE(bufoff, gbase, voff) do { const int so_ = (int)(unsigned)((const char*)(gbase) - base_##voff); _Pragma("unroll") for (int _i = 0; _i < 2; ++_i) \
;         __builtin_amdgcn_raw_ptr_buffer_load_lds(rs_##voff, (PG8_LAS unsigned*)(lds + (bufoff) + ldsw + _i * 8192), 16, (int)(voff)[_i], so_, 0, 0); } while (0)
; #define PG8_LDA(dst, b, h) do { _Pragma("unroll") for (int m = 0; m < 4; ++m) _Pragma("unroll") for (int k = 0; k < 2; ++k) dst[m][k] = *(const PG8_LAS bf16x8*)(lds + PG8_SA(b, h) + aoff + m * 2048 + k * 1024); } while (0)
; #define PG8_LDB(dst, b, h) do { _Pragma("unroll") for (int n = 0; n < 2; ++n) _Pragma("unroll") for (int k = 0; k < 2; ++k) dst[n][k] = *(const PG8_LAS bf16x8*)(lds + PG8_SB(b, h) + boff + n * 2048 + k * 1024); } while (0)
; #define PG8_MMA(ai, bj, At, Bt) do { __builtin_amdgcn_s_setprio(1); _Pragma("unroll") for (int m = 0; m < 4; ++m) _Pragma("unroll") for (int n = 0; n < 2; ++n) _Pragma("unroll") for (int k = 0; k < 2; ++k) \
;         acc[ai][bj][m][n] = __builtin_amdgcn_mfma_f32_16x16x32_bf16(Bt[n][k], At[m][k], acc[ai][bj][m][n], 0, 0, 0); __builtin_amdgcn_s_setprio(0); } while (0)
; #define PG8_WAIT_V(n) asm volatile("s_waitcnt vmcnt(" #n ")" ::: "memory")
; #define PG8_WAIT_L(n) asm volatile("s_waitcnt lgkmcnt(" #n ")" ::: "memory")
; #define PG8_BAR __builtin_amdgcn_s_barrier()
; #define PG8_SCHED __builtin_amdgcn_sched_barrier(0)
; template <class Epi, class Sched, bool ALIGN_EPI = false, bool SP2 = false>
; __device__ __forceinline__ void gemm_phase(PG8_LAS unsigned char* lds, const Gemm g, const Sched& S, const Epi& E, int tid_in) {
;     ...
;             PG8_LDB(B0, 0, 0); PG8_LDB(B1, 0, 1); PG8_SCHED; PG8_LDA(At, 0, 0); PG8_STAGE(PG8_SA(1, 1), a1 + hstepA, voffA);
;             PG8_WAIT_V(8); PG8_WAIT_L(0); PG8_BAR; PG8_MMA(0, 0, At, B0); PG8_MMA(0, 1, At, B1); PG8_BAR; PG8_SCHED;
;             PG8_LDA(At, 0, 1); PG8_STAGE(PG8_SB(0, 0), b2, voffB); PG8_STAGE(PG8_SB(0, 1), b2 + hstepB, voffB); PG8_STAGE(PG8_SA(0, 0), a2, voffA);
;             PG8_WAIT_V(8); PG8_WAIT_L(0); PG8_BAR; PG8_MMA(1, 0, At, B0); PG8_MMA(1, 1, At, B1); PG8_BAR; PG8_SCHED;
.LBB0_312:
	v_add_u32_e32 v0, 0x10000, v237
	ds_read_b128 v[130:133], v0
	ds_read_b128 v[134:137], v0 offset:1024
	ds_read_b128 v[138:141], v0 offset:2048
	ds_read_b128 v[142:145], v0 offset:3072
	v_add_u32_e32 v0, 0x14000, v237
	ds_read_b128 v[146:149], v0
	ds_read_b128 v[150:153], v0 offset:1024
	ds_read_b128 v[154:157], v0 offset:2048
	ds_read_b128 v[158:161], v0 offset:3072
	s_add_u32 s16, s12, 0x100
	s_addc_u32 s17, s13, 0
	s_sub_i32 s12, s12, s4
	s_add_i32 s12, s12, 0x80080
	s_sub_i32 s36, s12, 0x80000
	s_cmp_eq_u32 s23, 28
	s_cselect_b32 s13, s19, s16
	s_mov_b32 m0, s69
	ds_read_b128 v[162:165], v238
	ds_read_b128 v[166:169], v238 offset:1024
	ds_read_b128 v[170:173], v238 offset:2048
	ds_read_b128 v[174:177], v238 offset:3072
	ds_read_b128 v[178:181], v238 offset:4096
	ds_read_b128 v[182:185], v238 offset:5120
	ds_read_b128 v[186:189], v238 offset:6144
	ds_read_b128 v[190:193], v238 offset:7168
	s_mov_b32 m0, s78
	s_nop 0
	buffer_load_dwordx4 v211, s[4:7], s36 offen lds
	s_mov_b32 m0, s69
	s_nop 0
	buffer_load_dwordx4 v195, s[4:7], s12 offen lds
	s_mov_b32 m0, s67
	s_nop 0
	buffer_load_dwordx4 v211, s[4:7], s12 offen lds
	s_waitcnt vmcnt(8)
	s_waitcnt lgkmcnt(0)
	s_barrier
	s_setprio 1
	s_waitcnt lgkmcnt(0)
	v_mfma_f32_16x16x32_bf16 v[126:129], v[130:133], v[162:165], v[126:129]
	v_mfma_f32_16x16x32_bf16 v[122:125], v[138:141], v[162:165], v[122:125]
	v_mfma_f32_16x16x32_bf16 v[106:109], v[138:141], v[170:173], v[106:109]
	v_mfma_f32_16x16x32_bf16 v[110:113], v[130:133], v[170:173], v[110:113]
	v_mfma_f32_16x16x32_bf16 v[94:97], v[130:133], v[178:181], v[94:97]
	v_mfma_f32_16x16x32_bf16 v[90:93], v[138:141], v[178:181], v[90:93]
	v_mfma_f32_16x16x32_bf16 v[74:77], v[138:141], v[186:189], v[74:77]
	v_mfma_f32_16x16x32_bf16 v[78:81], v[130:133], v[186:189], v[78:81]
	v_mfma_f32_16x16x32_bf16 v[126:129], v[134:137], v[166:169], v[126:129]
	v_mfma_f32_16x16x32_bf16 v[122:125], v[142:145], v[166:169], v[122:125]
	v_mfma_f32_16x16x32_bf16 v[106:109], v[142:145], v[174:177], v[106:109]
	v_mfma_f32_16x16x32_bf16 v[110:113], v[134:137], v[174:177], v[110:113]
	v_mfma_f32_16x16x32_bf16 v[94:97], v[134:137], v[182:185], v[94:97]
	v_mfma_f32_16x16x32_bf16 v[90:93], v[142:145], v[182:185], v[90:93]
	v_mfma_f32_16x16x32_bf16 v[74:77], v[142:145], v[190:193], v[74:77]
	v_mfma_f32_16x16x32_bf16 v[78:81], v[134:137], v[190:193], v[78:81]
	s_setprio 0
	s_setprio 1
	v_mfma_f32_16x16x32_bf16 v[118:121], v[146:149], v[162:165], v[118:121]
	v_mfma_f32_16x16x32_bf16 v[114:117], v[154:157], v[162:165], v[114:117]
	v_mfma_f32_16x16x32_bf16 v[98:101], v[154:157], v[170:173], v[98:101]
	v_mfma_f32_16x16x32_bf16 v[102:105], v[146:149], v[170:173], v[102:105]
	v_mfma_f32_16x16x32_bf16 v[86:89], v[146:149], v[178:181], v[86:89]
	v_mfma_f32_16x16x32_bf16 v[82:85], v[154:157], v[178:181], v[82:85]
	v_mfma_f32_16x16x32_bf16 v[66:69], v[154:157], v[186:189], v[66:69]
	v_mfma_f32_16x16x32_bf16 v[70:73], v[146:149], v[186:189], v[70:73]
	v_mfma_f32_16x16x32_bf16 v[118:121], v[150:153], v[166:169], v[118:121]
	v_mfma_f32_16x16x32_bf16 v[114:117], v[158:161], v[166:169], v[114:117]
	v_mfma_f32_16x16x32_bf16 v[98:101], v[158:161], v[174:177], v[98:101]
	v_mfma_f32_16x16x32_bf16 v[102:105], v[150:153], v[174:177], v[102:105]
	v_mfma_f32_16x16x32_bf16 v[86:89], v[150:153], v[182:185], v[86:89]
	v_mfma_f32_16x16x32_bf16 v[82:85], v[158:161], v[182:185], v[82:85]
	v_mfma_f32_16x16x32_bf16 v[66:69], v[158:161], v[190:193], v[66:69]
	v_mfma_f32_16x16x32_bf16 v[70:73], v[150:153], v[190:193], v[70:73]
	s_setprio 0
	s_barrier
	s_cselect_b32 s12, s15, s20
	s_mov_b32 m0, s61
	s_mov_b32 s42, s6
	s_mov_b32 s43, s7
	s_sub_i32 s12, s12, s40
	ds_read_b128 v[162:165], v238 offset:16384
	ds_read_b128 v[166:169], v238 offset:17408
	ds_read_b128 v[170:173], v238 offset:18432
	ds_read_b128 v[174:177], v238 offset:19456
	ds_read_b128 v[178:181], v238 offset:20480
	ds_read_b128 v[182:185], v238 offset:21504
	ds_read_b128 v[186:189], v238 offset:22528
	ds_read_b128 v[190:193], v238 offset:23552
	buffer_load_dwordx4 v207, s[40:43], s12 offen lds
	s_mov_b32 m0, s62
	s_add_i32 s36, s12, 0x80000
	buffer_load_dwordx4 v224, s[40:43], s12 offen lds
	s_mov_b32 m0, s63
	s_sub_i32 s13, s13, s4
	buffer_load_dwordx4 v207, s[40:43], s36 offen lds
	s_mov_b32 m0, s71
	s_nop 0
	buffer_load_dwordx4 v224, s[40:43], s36 offen lds
	s_mov_b32 m0, s53
	s_nop 0
	buffer_load_dwordx4 v195, s[4:7], s13 offen lds
	s_waitcnt vmcnt(7)
	s_waitcnt lgkmcnt(0)
	s_barrier
	s_setprio 1
	s_waitcnt lgkmcnt(0)
	v_mfma_f32_16x16x32_bf16 v[62:65], v[130:133], v[162:165], v[62:65]
	v_mfma_f32_16x16x32_bf16 v[58:61], v[138:141], v[162:165], v[58:61]
	v_mfma_f32_16x16x32_bf16 v[42:45], v[138:141], v[170:173], v[42:45]
	v_mfma_f32_16x16x32_bf16 v[46:49], v[130:133], v[170:173], v[46:49]
	v_mfma_f32_16x16x32_bf16 v[30:33], v[130:133], v[178:181], v[30:33]
	v_mfma_f32_16x16x32_bf16 v[26:29], v[138:141], v[178:181], v[26:29]
	v_mfma_f32_16x16x32_bf16 v[10:13], v[138:141], v[186:189], v[10:13]
	v_mfma_f32_16x16x32_bf16 v[14:17], v[130:133], v[186:189], v[14:17]
	v_mfma_f32_16x16x32_bf16 v[62:65], v[134:137], v[166:169], v[62:65]
	v_mfma_f32_16x16x32_bf16 v[58:61], v[142:145], v[166:169], v[58:61]
	v_mfma_f32_16x16x32_bf16 v[42:45], v[142:145], v[174:177], v[42:45]
	v_mfma_f32_16x16x32_bf16 v[46:49], v[134:137], v[174:177], v[46:49]
	v_mfma_f32_16x16x32_bf16 v[30:33], v[134:137], v[182:185], v[30:33]
	v_mfma_f32_16x16x32_bf16 v[26:29], v[142:145], v[182:185], v[26:29]
	v_mfma_f32_16x16x32_bf16 v[10:13], v[142:145], v[190:193], v[10:13]
	v_mfma_f32_16x16x32_bf16 v[14:17], v[134:137], v[190:193], v[14:17]
	s_setprio 0
	s_setprio 1
	v_mfma_f32_16x16x32_bf16 v[54:57], v[146:149], v[162:165], v[54:57]
	v_mfma_f32_16x16x32_bf16 v[50:53], v[154:157], v[162:165], v[50:53]
	v_mfma_f32_16x16x32_bf16 v[34:37], v[154:157], v[170:173], v[34:37]
	v_mfma_f32_16x16x32_bf16 v[38:41], v[146:149], v[170:173], v[38:41]
	v_mfma_f32_16x16x32_bf16 v[22:25], v[146:149], v[178:181], v[22:25]
	v_mfma_f32_16x16x32_bf16 v[18:21], v[154:157], v[178:181], v[18:21]
	v_mfma_f32_16x16x32_bf16 v[2:5], v[154:157], v[186:189], v[2:5]
	v_mfma_f32_16x16x32_bf16 v[6:9], v[146:149], v[186:189], v[6:9]
	v_mfma_f32_16x16x32_bf16 v[54:57], v[150:153], v[166:169], v[54:57]
	v_mfma_f32_16x16x32_bf16 v[50:53], v[158:161], v[166:169], v[50:53]
	v_mfma_f32_16x16x32_bf16 v[34:37], v[158:161], v[174:177], v[34:37]
	v_mfma_f32_16x16x32_bf16 v[38:41], v[150:153], v[174:177], v[38:41]
	v_mfma_f32_16x16x32_bf16 v[22:25], v[150:153], v[182:185], v[22:25]
	v_mfma_f32_16x16x32_bf16 v[18:21], v[158:161], v[182:185], v[18:21]
	v_mfma_f32_16x16x32_bf16 v[2:5], v[158:161], v[190:193], v[2:5]
	v_mfma_f32_16x16x32_bf16 v[6:9], v[150:153], v[190:193], v[6:9]
	s_setprio 0
	s_barrier
; #define PG8_STAGE(bufoff, gbase, voff) do { const int so_ = (int)(unsigned)((const char*)(gbase) - base_##voff); _Pragma("unroll") for (int _i = 0; _i < 2; ++_i) \
;         __builtin_amdgcn_raw_ptr_buffer_load_lds(rs_##voff, (PG8_LAS unsigned*)(lds + (bufoff) + ldsw + _i * 8192), 16, (int)(voff)[_i], so_, 0, 0); } while (0)
; #define PG8_LDA(dst, b, h) do { _Pragma("unroll") for (int m = 0; m < 4; ++m) _Pragma("unroll") for (int k = 0; k < 2; ++k) dst[m][k] = *(const PG8_LAS bf16x8*)(lds + PG8_SA(b, h) + aoff + m * 2048 + k * 1024); } while (0)
; #define PG8_LDB(dst, b, h) do { _Pragma("unroll") for (int n = 0; n < 2; ++n) _Pragma("unroll") for (int k = 0; k < 2; ++k) dst[n][k] = *(const PG8_LAS bf16x8*)(lds + PG8_SB(b, h) + boff + n * 2048 + k * 1024); } while (0)
; #define PG8_MMA(ai, bj, At, Bt) do { __builtin_amdgcn_s_setprio(1); _Pragma("unroll") for (int m = 0; m < 4; ++m) _Pragma("unroll") for (int n = 0; n < 2; ++n) _Pragma("unroll") for (int k = 0; k < 2; ++k) \
;         acc[ai][bj][m][n] = __builtin_amdgcn_mfma_f32_16x16x32_bf16(Bt[n][k], At[m][k], acc[ai][bj][m][n], 0, 0, 0); __builtin_amdgcn_s_setprio(0); } while (0)
; #define PG8_WAIT_V(n) asm volatile("s_waitcnt vmcnt(" #n ")" ::: "memory")
; #define PG8_WAIT_L(n) asm volatile("s_waitcnt lgkmcnt(" #n ")" ::: "memory")
; #define PG8_BAR __builtin_amdgcn_s_barrier()
; #define PG8_SCHED __builtin_amdgcn_sched_barrier(0)
; template <class Epi, class Sched, bool ALIGN_EPI = false, bool SP2 = false>
; __device__ __forceinline__ void gemm_phase(PG8_LAS unsigned char* lds, const Gemm g, const Sched& S, const Epi& E, int tid_in) {
;     ...
;             PG8_LDB(B0, 1, 0); PG8_LDB(B1, 1, 1); PG8_SCHED; PG8_LDA(At, 1, 0); PG8_STAGE(PG8_SA(0, 1), a2 + hstepA, voffA);
;             PG8_WAIT_V(8); PG8_WAIT_L(0); PG8_BAR; PG8_MMA(0, 0, At, B0); PG8_MMA(0, 1, At, B1); PG8_BAR; PG8_SCHED;
;             PG8_LDA(At, 1, 1); PG8_STAGE(PG8_SB(1, 0), b3, voffB); PG8_STAGE(PG8_SB(1, 1), b3 + hstepB, voffB); PG8_STAGE(PG8_SA(1, 0), a3, voffA);
;             PG8_WAIT_V(8); PG8_WAIT_L(0); PG8_BAR; PG8_MMA(1, 0, At, B0); PG8_MMA(1, 1, At, B1); PG8_BAR; PG8_SCHED;
	v_add_u32_e32 v0, 0x18000, v237
	ds_read_b128 v[130:133], v0
	ds_read_b128 v[134:137], v0 offset:1024
	ds_read_b128 v[138:141], v0 offset:2048
	ds_read_b128 v[142:145], v0 offset:3072
	v_add_u32_e32 v0, 0x1c000, v237
	ds_read_b128 v[146:149], v0
	ds_read_b128 v[150:153], v0 offset:1024
	ds_read_b128 v[154:157], v0 offset:2048
	ds_read_b128 v[158:161], v0 offset:3072
	s_add_i32 s36, s13, 0x80000
	s_mov_b32 m0, s73
	ds_read_b128 v[162:165], v238 offset:32768
	ds_read_b128 v[166:169], v238 offset:33792
	ds_read_b128 v[170:173], v238 offset:34816
	ds_read_b128 v[174:177], v238 offset:35840
	ds_read_b128 v[178:181], v238 offset:36864
	ds_read_b128 v[182:185], v238 offset:37888
	ds_read_b128 v[186:189], v238 offset:38912
	ds_read_b128 v[190:193], v238 offset:39936
	s_mov_b32 m0, s72
	s_nop 0
	buffer_load_dwordx4 v211, s[4:7], s13 offen lds
	s_mov_b32 m0, s73
	s_nop 0
	buffer_load_dwordx4 v195, s[4:7], s36 offen lds
	s_mov_b32 m0, s74
	s_nop 0
	buffer_load_dwordx4 v211, s[4:7], s36 offen lds
	s_waitcnt vmcnt(8)
	s_waitcnt lgkmcnt(0)
	s_barrier
	s_setprio 1
	s_waitcnt lgkmcnt(0)
	v_mfma_f32_16x16x32_bf16 v[126:129], v[130:133], v[162:165], v[126:129]
	v_mfma_f32_16x16x32_bf16 v[122:125], v[138:141], v[162:165], v[122:125]
	v_mfma_f32_16x16x32_bf16 v[106:109], v[138:141], v[170:173], v[106:109]
	v_mfma_f32_16x16x32_bf16 v[110:113], v[130:133], v[170:173], v[110:113]
	v_mfma_f32_16x16x32_bf16 v[94:97], v[130:133], v[178:181], v[94:97]
	v_mfma_f32_16x16x32_bf16 v[90:93], v[138:141], v[178:181], v[90:93]
	v_mfma_f32_16x16x32_bf16 v[74:77], v[138:141], v[186:189], v[74:77]
	v_mfma_f32_16x16x32_bf16 v[78:81], v[130:133], v[186:189], v[78:81]
	v_mfma_f32_16x16x32_bf16 v[126:129], v[134:137], v[166:169], v[126:129]
	v_mfma_f32_16x16x32_bf16 v[122:125], v[142:145], v[166:169], v[122:125]
	v_mfma_f32_16x16x32_bf16 v[106:109], v[142:145], v[174:177], v[106:109]
	v_mfma_f32_16x16x32_bf16 v[110:113], v[134:137], v[174:177], v[110:113]
	v_mfma_f32_16x16x32_bf16 v[94:97], v[134:137], v[182:185], v[94:97]
	v_mfma_f32_16x16x32_bf16 v[90:93], v[142:145], v[182:185], v[90:93]
	v_mfma_f32_16x16x32_bf16 v[74:77], v[142:145], v[190:193], v[74:77]
	v_mfma_f32_16x16x32_bf16 v[78:81], v[134:137], v[190:193], v[78:81]
	s_setprio 0
	s_setprio 1
	v_mfma_f32_16x16x32_bf16 v[118:121], v[146:149], v[162:165], v[118:121]
	v_mfma_f32_16x16x32_bf16 v[114:117], v[154:157], v[162:165], v[114:117]
	v_mfma_f32_16x16x32_bf16 v[98:101], v[154:157], v[170:173], v[98:101]
	v_mfma_f32_16x16x32_bf16 v[102:105], v[146:149], v[170:173], v[102:105]
	v_mfma_f32_16x16x32_bf16 v[86:89], v[146:149], v[178:181], v[86:89]
	v_mfma_f32_16x16x32_bf16 v[82:85], v[154:157], v[178:181], v[82:85]
	v_mfma_f32_16x16x32_bf16 v[66:69], v[154:157], v[186:189], v[66:69]
	v_mfma_f32_16x16x32_bf16 v[70:73], v[146:149], v[186:189], v[70:73]
	v_mfma_f32_16x16x32_bf16 v[118:121], v[150:153], v[166:169], v[118:121]
	v_mfma_f32_16x16x32_bf16 v[114:117], v[158:161], v[166:169], v[114:117]
	v_mfma_f32_16x16x32_bf16 v[98:101], v[158:161], v[174:177], v[98:101]
	v_mfma_f32_16x16x32_bf16 v[102:105], v[150:153], v[174:177], v[102:105]
	v_mfma_f32_16x16x32_bf16 v[86:89], v[150:153], v[182:185], v[86:89]
	v_mfma_f32_16x16x32_bf16 v[82:85], v[158:161], v[182:185], v[82:85]
	v_mfma_f32_16x16x32_bf16 v[66:69], v[158:161], v[190:193], v[66:69]
	v_mfma_f32_16x16x32_bf16 v[70:73], v[150:153], v[190:193], v[70:73]
	s_setprio 0
	s_barrier
	s_mov_b32 m0, s75
	s_add_i32 s36, s12, 0x80
	ds_read_b128 v[162:165], v238 offset:49152
	ds_read_b128 v[166:169], v238 offset:50176
	ds_read_b128 v[170:173], v238 offset:51200
	ds_read_b128 v[174:177], v238 offset:52224
	ds_read_b128 v[178:181], v238 offset:53248
	ds_read_b128 v[182:185], v238 offset:54272
	ds_read_b128 v[186:189], v238 offset:55296
	ds_read_b128 v[190:193], v238 offset:56320
	buffer_load_dwordx4 v207, s[40:43], s36 offen lds
	s_mov_b32 m0, s76
	s_add_i32 s12, s12, 0x80080
	buffer_load_dwordx4 v224, s[40:43], s36 offen lds
	s_mov_b32 m0, s79
	s_addk_i32 s13, 0x80
	buffer_load_dwordx4 v207, s[40:43], s12 offen lds
	s_mov_b32 m0, s68
	s_nop 0
	buffer_load_dwordx4 v224, s[40:43], s12 offen lds
	s_mov_b32 m0, s77
	s_nop 0
	buffer_load_dwordx4 v195, s[4:7], s13 offen lds
	s_waitcnt vmcnt(7)
	s_waitcnt lgkmcnt(0)
	s_barrier
	s_setprio 1
	s_waitcnt lgkmcnt(0)
	v_mfma_f32_16x16x32_bf16 v[62:65], v[130:133], v[162:165], v[62:65]
	v_mfma_f32_16x16x32_bf16 v[58:61], v[138:141], v[162:165], v[58:61]
	v_mfma_f32_16x16x32_bf16 v[42:45], v[138:141], v[170:173], v[42:45]
	v_mfma_f32_16x16x32_bf16 v[46:49], v[130:133], v[170:173], v[46:49]
	v_mfma_f32_16x16x32_bf16 v[30:33], v[130:133], v[178:181], v[30:33]
	v_mfma_f32_16x16x32_bf16 v[26:29], v[138:141], v[178:181], v[26:29]
	v_mfma_f32_16x16x32_bf16 v[10:13], v[138:141], v[186:189], v[10:13]
	v_mfma_f32_16x16x32_bf16 v[14:17], v[130:133], v[186:189], v[14:17]
	v_mfma_f32_16x16x32_bf16 v[62:65], v[134:137], v[166:169], v[62:65]
	v_mfma_f32_16x16x32_bf16 v[58:61], v[142:145], v[166:169], v[58:61]
	v_mfma_f32_16x16x32_bf16 v[42:45], v[142:145], v[174:177], v[42:45]
	v_mfma_f32_16x16x32_bf16 v[46:49], v[134:137], v[174:177], v[46:49]
	v_mfma_f32_16x16x32_bf16 v[30:33], v[134:137], v[182:185], v[30:33]
	v_mfma_f32_16x16x32_bf16 v[26:29], v[142:145], v[182:185], v[26:29]
	v_mfma_f32_16x16x32_bf16 v[10:13], v[142:145], v[190:193], v[10:13]
	v_mfma_f32_16x16x32_bf16 v[14:17], v[134:137], v[190:193], v[14:17]
	s_setprio 0
	s_setprio 1
	v_mfma_f32_16x16x32_bf16 v[54:57], v[146:149], v[162:165], v[54:57]
	v_mfma_f32_16x16x32_bf16 v[50:53], v[154:157], v[162:165], v[50:53]
	v_mfma_f32_16x16x32_bf16 v[34:37], v[154:157], v[170:173], v[34:37]
	v_mfma_f32_16x16x32_bf16 v[38:41], v[146:149], v[170:173], v[38:41]
	v_mfma_f32_16x16x32_bf16 v[22:25], v[146:149], v[178:181], v[22:25]
	v_mfma_f32_16x16x32_bf16 v[18:21], v[154:157], v[178:181], v[18:21]
	v_mfma_f32_16x16x32_bf16 v[2:5], v[154:157], v[186:189], v[2:5]
	v_mfma_f32_16x16x32_bf16 v[6:9], v[146:149], v[186:189], v[6:9]
	v_mfma_f32_16x16x32_bf16 v[54:57], v[150:153], v[166:169], v[54:57]
	v_mfma_f32_16x16x32_bf16 v[50:53], v[158:161], v[166:169], v[50:53]
	v_mfma_f32_16x16x32_bf16 v[34:37], v[158:161], v[174:177], v[34:37]
	v_mfma_f32_16x16x32_bf16 v[38:41], v[150:153], v[174:177], v[38:41]
	v_mfma_f32_16x16x32_bf16 v[22:25], v[150:153], v[182:185], v[22:25]
	v_mfma_f32_16x16x32_bf16 v[18:21], v[158:161], v[182:185], v[18:21]
	v_mfma_f32_16x16x32_bf16 v[2:5], v[158:161], v[190:193], v[2:5]
	v_mfma_f32_16x16x32_bf16 v[6:9], v[150:153], v[190:193], v[6:9]
	s_setprio 0
	s_barrier
	s_add_i32 s23, s23, 2
	s_add_u32 s20, s20, 0x100
	s_addc_u32 s21, s21, 0
	s_cmp_gt_u32 s23, 29
	s_mov_b64 s[12:13], s[16:17]
	s_cbranch_scc0 .LBB0_312
	s_and_b64 vcc, exec, s[48:49]
	s_cbranch_vccz .LBB0_315
	s_barrier

; #define PG8_STAGE(bufoff, gbase, voff) do { const int so_ = (int)(unsigned)((const char*)(gbase) - base_##voff); _Pragma("unroll") for (int _i = 0; _i < 2; ++_i) \
;         __builtin_amdgcn_raw_ptr_buffer_load_lds(rs_##voff, (PG8_LAS unsigned*)(lds + (bufoff) + ldsw + _i * 8192), 16, (int)(voff)[_i], so_, 0, 0); } while (0)
; #define PG8_LDA(dst, b, h) do { _Pragma("unroll") for (int m = 0; m < 4; ++m) _Pragma("unroll") for (int k = 0; k < 2; ++k) dst[m][k] = *(const PG8_LAS bf16x8*)(lds + PG8_SA(b, h) + aoff + m * 2048 + k * 1024); } while (0)
; #define PG8_LDB(dst, b, h) do { _Pragma("unroll") for (int n = 0; n < 2; ++n) _Pragma("unroll") for (int k = 0; k < 2; ++k) dst[n][k] = *(const PG8_LAS bf16x8*)(lds + PG8_SB(b, h) + boff + n * 2048 + k * 1024); } while (0)
; #define PG8_MMA(ai, bj, At, Bt) do { __builtin_amdgcn_s_setprio(1); _Pragma("unroll") for (int m = 0; m < 4; ++m) _Pragma("unroll") for (int n = 0; n < 2; ++n) _Pragma("unroll") for (int k = 0; k < 2; ++k) \
;         acc[ai][bj][m][n] = __builtin_amdgcn_mfma_f32_16x16x32_bf16(Bt[n][k], At[m][k], acc[ai][bj][m][n], 0, 0, 0); __builtin_amdgcn_s_setprio(0); } while (0)
; #define PG8_WAIT_V(n) asm volatile("s_waitcnt vmcnt(" #n ")" ::: "memory")
; #define PG8_WAIT_L(n) asm volatile("s_waitcnt lgkmcnt(" #n ")" ::: "memory")
; #define PG8_BAR __builtin_amdgcn_s_barrier()
; #define PG8_SCHED __builtin_amdgcn_sched_barrier(0)
; template <class Epi, class Sched, bool ALIGN_EPI = false, bool SP2 = false>
; __device__ __forceinline__ void gemm_phase(PG8_LAS unsigned char* lds, const Gemm g, const Sched& S, const Epi& E, int tid_in) {
;     ...
;             PG8_LDB(B0, 0, 0); PG8_LDB(B1, 0, 1); PG8_SCHED; PG8_LDA(At, 0, 0); PG8_STAGE(PG8_SA(1, 1), a1 + hstepA, voffA);
;             PG8_WAIT_V(8); PG8_WAIT_L(0); PG8_BAR; PG8_MMA(0, 0, At, B0); PG8_MMA(0, 1, At, B1); PG8_BAR; PG8_SCHED;
;             PG8_LDA(At, 0, 1); PG8_STAGE(PG8_SB(0, 0), b2, voffB); PG8_STAGE(PG8_SB(0, 1), b2 + hstepB, voffB); PG8_STAGE(PG8_SA(0, 0), a2, voffA);
;             PG8_WAIT_V(8); PG8_WAIT_L(0); PG8_BAR; PG8_MMA(1, 0, At, B0); PG8_MMA(1, 1, At, B1); PG8_BAR; PG8_SCHED;
.LBB0_1037:
	v_add_u32_e32 v0, 0x10000, v236
	ds_read_b128 v[132:135], v0
	ds_read_b128 v[136:139], v0 offset:1024
	ds_read_b128 v[140:143], v0 offset:2048
	ds_read_b128 v[144:147], v0 offset:3072
	v_add_u32_e32 v0, 0x14000, v236
	ds_read_b128 v[148:151], v0
	ds_read_b128 v[152:155], v0 offset:1024
	ds_read_b128 v[156:159], v0 offset:2048
	ds_read_b128 v[160:163], v0 offset:3072
	s_add_u32 s16, s12, 0x100
	s_addc_u32 s17, s13, 0
	s_sub_i32 s12, s12, s4
	s_add_i32 s12, s12, 0xc0080
	s_sub_i32 s39, s12, 0xc0000
	s_cmp_eq_u32 s38, 12
	s_cselect_b32 s13, s24, s16
	s_mov_b32 m0, s76
	ds_read_b128 v[164:167], v237
	ds_read_b128 v[168:171], v237 offset:1024
	ds_read_b128 v[172:175], v237 offset:2048
	ds_read_b128 v[176:179], v237 offset:3072
	ds_read_b128 v[180:183], v237 offset:4096
	ds_read_b128 v[184:187], v237 offset:5120
	ds_read_b128 v[188:191], v237 offset:6144
	ds_read_b128 v[192:195], v237 offset:7168
	s_mov_b32 m0, s73
	s_nop 0
	buffer_load_dwordx4 v222, s[4:7], s39 offen lds
	s_mov_b32 m0, s76
	s_nop 0
	buffer_load_dwordx4 v220, s[4:7], s12 offen lds
	s_mov_b32 m0, s77
	s_nop 0
	buffer_load_dwordx4 v222, s[4:7], s12 offen lds
	s_waitcnt vmcnt(8)
	s_waitcnt lgkmcnt(0)
	s_barrier
	s_setprio 1
	s_waitcnt lgkmcnt(0)
	v_mfma_f32_16x16x32_bf16 v[128:131], v[132:135], v[164:167], v[128:131]
	v_mfma_f32_16x16x32_bf16 v[124:127], v[140:143], v[164:167], v[124:127]
	v_mfma_f32_16x16x32_bf16 v[116:119], v[140:143], v[172:175], v[116:119]
	v_mfma_f32_16x16x32_bf16 v[120:123], v[132:135], v[172:175], v[120:123]
	v_mfma_f32_16x16x32_bf16 v[112:115], v[132:135], v[180:183], v[112:115]
	v_mfma_f32_16x16x32_bf16 v[108:111], v[140:143], v[180:183], v[108:111]
	v_mfma_f32_16x16x32_bf16 v[100:103], v[140:143], v[188:191], v[100:103]
	v_mfma_f32_16x16x32_bf16 v[104:107], v[132:135], v[188:191], v[104:107]
	v_mfma_f32_16x16x32_bf16 v[128:131], v[136:139], v[168:171], v[128:131]
	v_mfma_f32_16x16x32_bf16 v[124:127], v[144:147], v[168:171], v[124:127]
	v_mfma_f32_16x16x32_bf16 v[116:119], v[144:147], v[176:179], v[116:119]
	v_mfma_f32_16x16x32_bf16 v[120:123], v[136:139], v[176:179], v[120:123]
	v_mfma_f32_16x16x32_bf16 v[112:115], v[136:139], v[184:187], v[112:115]
	v_mfma_f32_16x16x32_bf16 v[108:111], v[144:147], v[184:187], v[108:111]
	v_mfma_f32_16x16x32_bf16 v[100:103], v[144:147], v[192:195], v[100:103]
	v_mfma_f32_16x16x32_bf16 v[104:107], v[136:139], v[192:195], v[104:107]
	s_setprio 0
	s_setprio 1
	v_mfma_f32_16x16x32_bf16 v[96:99], v[148:151], v[164:167], v[96:99]
	v_mfma_f32_16x16x32_bf16 v[92:95], v[156:159], v[164:167], v[92:95]
	v_mfma_f32_16x16x32_bf16 v[84:87], v[156:159], v[172:175], v[84:87]
	v_mfma_f32_16x16x32_bf16 v[88:91], v[148:151], v[172:175], v[88:91]
	v_mfma_f32_16x16x32_bf16 v[80:83], v[148:151], v[180:183], v[80:83]
	v_mfma_f32_16x16x32_bf16 v[76:79], v[156:159], v[180:183], v[76:79]
	v_mfma_f32_16x16x32_bf16 v[68:71], v[156:159], v[188:191], v[68:71]
	v_mfma_f32_16x16x32_bf16 v[72:75], v[148:151], v[188:191], v[72:75]
	v_mfma_f32_16x16x32_bf16 v[96:99], v[152:155], v[168:171], v[96:99]
	v_mfma_f32_16x16x32_bf16 v[92:95], v[160:163], v[168:171], v[92:95]
	v_mfma_f32_16x16x32_bf16 v[84:87], v[160:163], v[176:179], v[84:87]
	v_mfma_f32_16x16x32_bf16 v[88:91], v[152:155], v[176:179], v[88:91]
	v_mfma_f32_16x16x32_bf16 v[80:83], v[152:155], v[184:187], v[80:83]
	v_mfma_f32_16x16x32_bf16 v[76:79], v[160:163], v[184:187], v[76:79]
	v_mfma_f32_16x16x32_bf16 v[68:71], v[160:163], v[192:195], v[68:71]
	v_mfma_f32_16x16x32_bf16 v[72:75], v[152:155], v[192:195], v[72:75]
	s_setprio 0
	s_barrier
	s_cselect_b32 s12, s18, s19
	s_mov_b32 m0, s26
	s_mov_b32 s46, s6
	s_mov_b32 s47, s7
	s_sub_i32 s12, s12, s44
	ds_read_b128 v[164:167], v237 offset:16384
	ds_read_b128 v[168:171], v237 offset:17408
	ds_read_b128 v[172:175], v237 offset:18432
	ds_read_b128 v[176:179], v237 offset:19456
	ds_read_b128 v[180:183], v237 offset:20480
	ds_read_b128 v[184:187], v237 offset:21504
	ds_read_b128 v[188:191], v237 offset:22528
	ds_read_b128 v[192:195], v237 offset:23552
	buffer_load_dwordx4 v221, s[44:47], s12 offen lds
	s_mov_b32 m0, s53
	s_add_i32 s39, s12, 0x40000
	buffer_load_dwordx4 v223, s[44:47], s12 offen lds
	s_mov_b32 m0, s60
	s_sub_i32 s13, s13, s4
	buffer_load_dwordx4 v221, s[44:47], s39 offen lds
	s_mov_b32 m0, s61
	s_nop 0
	buffer_load_dwordx4 v223, s[44:47], s39 offen lds
	s_mov_b32 m0, s21
	s_nop 0
	buffer_load_dwordx4 v220, s[4:7], s13 offen lds
	s_waitcnt vmcnt(7)
	s_waitcnt lgkmcnt(0)
	s_barrier
	s_setprio 1
	s_waitcnt lgkmcnt(0)
	v_mfma_f32_16x16x32_bf16 v[64:67], v[132:135], v[164:167], v[64:67]
	v_mfma_f32_16x16x32_bf16 v[60:63], v[140:143], v[164:167], v[60:63]
	v_mfma_f32_16x16x32_bf16 v[52:55], v[140:143], v[172:175], v[52:55]
	v_mfma_f32_16x16x32_bf16 v[56:59], v[132:135], v[172:175], v[56:59]
	v_mfma_f32_16x16x32_bf16 v[48:51], v[132:135], v[180:183], v[48:51]
	v_mfma_f32_16x16x32_bf16 v[44:47], v[140:143], v[180:183], v[44:47]
	v_mfma_f32_16x16x32_bf16 v[36:39], v[140:143], v[188:191], v[36:39]
	v_mfma_f32_16x16x32_bf16 v[40:43], v[132:135], v[188:191], v[40:43]
	v_mfma_f32_16x16x32_bf16 v[64:67], v[136:139], v[168:171], v[64:67]
	v_mfma_f32_16x16x32_bf16 v[60:63], v[144:147], v[168:171], v[60:63]
	v_mfma_f32_16x16x32_bf16 v[52:55], v[144:147], v[176:179], v[52:55]
	v_mfma_f32_16x16x32_bf16 v[56:59], v[136:139], v[176:179], v[56:59]
	v_mfma_f32_16x16x32_bf16 v[48:51], v[136:139], v[184:187], v[48:51]
	v_mfma_f32_16x16x32_bf16 v[44:47], v[144:147], v[184:187], v[44:47]
	v_mfma_f32_16x16x32_bf16 v[36:39], v[144:147], v[192:195], v[36:39]
	v_mfma_f32_16x16x32_bf16 v[40:43], v[136:139], v[192:195], v[40:43]
	s_setprio 0
	s_setprio 1
	v_mfma_f32_16x16x32_bf16 v[32:35], v[148:151], v[164:167], v[32:35]
	v_mfma_f32_16x16x32_bf16 v[28:31], v[156:159], v[164:167], v[28:31]
	v_mfma_f32_16x16x32_bf16 v[20:23], v[156:159], v[172:175], v[20:23]
	v_mfma_f32_16x16x32_bf16 v[24:27], v[148:151], v[172:175], v[24:27]
	v_mfma_f32_16x16x32_bf16 v[16:19], v[148:151], v[180:183], v[16:19]
	v_mfma_f32_16x16x32_bf16 v[12:15], v[156:159], v[180:183], v[12:15]
	v_mfma_f32_16x16x32_bf16 v[2:5], v[156:159], v[188:191], v[4:7]
	v_mfma_f32_16x16x32_bf16 v[8:11], v[148:151], v[188:191], v[8:11]
	v_mfma_f32_16x16x32_bf16 v[32:35], v[152:155], v[168:171], v[32:35]
	v_mfma_f32_16x16x32_bf16 v[28:31], v[160:163], v[168:171], v[28:31]
	v_mfma_f32_16x16x32_bf16 v[20:23], v[160:163], v[176:179], v[20:23]
	v_mfma_f32_16x16x32_bf16 v[24:27], v[152:155], v[176:179], v[24:27]
	v_mfma_f32_16x16x32_bf16 v[16:19], v[152:155], v[184:187], v[16:19]
	v_mfma_f32_16x16x32_bf16 v[12:15], v[160:163], v[184:187], v[12:15]
	v_mfma_f32_16x16x32_bf16 v[2:5], v[160:163], v[192:195], v[2:5]
	v_mfma_f32_16x16x32_bf16 v[8:11], v[152:155], v[192:195], v[8:11]
	s_setprio 0
	s_barrier
; #define PG8_STAGE(bufoff, gbase, voff) do { const int so_ = (int)(unsigned)((const char*)(gbase) - base_##voff); _Pragma("unroll") for (int _i = 0; _i < 2; ++_i) \
;         __builtin_amdgcn_raw_ptr_buffer_load_lds(rs_##voff, (PG8_LAS unsigned*)(lds + (bufoff) + ldsw + _i * 8192), 16, (int)(voff)[_i], so_, 0, 0); } while (0)
; #define PG8_LDA(dst, b, h) do { _Pragma("unroll") for (int m = 0; m < 4; ++m) _Pragma("unroll") for (int k = 0; k < 2; ++k) dst[m][k] = *(const PG8_LAS bf16x8*)(lds + PG8_SA(b, h) + aoff + m * 2048 + k * 1024); } while (0)
; #define PG8_LDB(dst, b, h) do { _Pragma("unroll") for (int n = 0; n < 2; ++n) _Pragma("unroll") for (int k = 0; k < 2; ++k) dst[n][k] = *(const PG8_LAS bf16x8*)(lds + PG8_SB(b, h) + boff + n * 2048 + k * 1024); } while (0)
; #define PG8_MMA(ai, bj, At, Bt) do { __builtin_amdgcn_s_setprio(1); _Pragma("unroll") for (int m = 0; m < 4; ++m) _Pragma("unroll") for (int n = 0; n < 2; ++n) _Pragma("unroll") for (int k = 0; k < 2; ++k) \
;         acc[ai][bj][m][n] = __builtin_amdgcn_mfma_f32_16x16x32_bf16(Bt[n][k], At[m][k], acc[ai][bj][m][n], 0, 0, 0); __builtin_amdgcn_s_setprio(0); } while (0)
; #define PG8_WAIT_V(n) asm volatile("s_waitcnt vmcnt(" #n ")" ::: "memory")
; #define PG8_WAIT_L(n) asm volatile("s_waitcnt lgkmcnt(" #n ")" ::: "memory")
; #define PG8_BAR __builtin_amdgcn_s_barrier()
; #define PG8_SCHED __builtin_amdgcn_sched_barrier(0)
; template <class Epi, class Sched, bool ALIGN_EPI = false, bool SP2 = false>
; __device__ __forceinline__ void gemm_phase(PG8_LAS unsigned char* lds, const Gemm g, const Sched& S, const Epi& E, int tid_in) {
;     ...
;             PG8_LDB(B0, 1, 0); PG8_LDB(B1, 1, 1); PG8_SCHED; PG8_LDA(At, 1, 0); PG8_STAGE(PG8_SA(0, 1), a2 + hstepA, voffA);
;             PG8_WAIT_V(8); PG8_WAIT_L(0); PG8_BAR; PG8_MMA(0, 0, At, B0); PG8_MMA(0, 1, At, B1); PG8_BAR; PG8_SCHED;
;             PG8_LDA(At, 1, 1); PG8_STAGE(PG8_SB(1, 0), b3, voffB); PG8_STAGE(PG8_SB(1, 1), b3 + hstepB, voffB); PG8_STAGE(PG8_SA(1, 0), a3, voffA);
;             PG8_WAIT_V(8); PG8_WAIT_L(0); PG8_BAR; PG8_MMA(1, 0, At, B0); PG8_MMA(1, 1, At, B1); PG8_BAR; PG8_SCHED;
	v_add_u32_e32 v0, 0x18000, v236
	ds_read_b128 v[132:135], v0
	ds_read_b128 v[136:139], v0 offset:1024
	ds_read_b128 v[140:143], v0 offset:2048
	ds_read_b128 v[144:147], v0 offset:3072
	v_add_u32_e32 v0, 0x1c000, v236
	ds_read_b128 v[148:151], v0
	ds_read_b128 v[152:155], v0 offset:1024
	ds_read_b128 v[156:159], v0 offset:2048
	ds_read_b128 v[160:163], v0 offset:3072
	s_add_i32 s39, s13, 0xc0000
	s_mov_b32 m0, s63
	ds_read_b128 v[164:167], v237 offset:32768
	ds_read_b128 v[168:171], v237 offset:33792
	ds_read_b128 v[172:175], v237 offset:34816
	ds_read_b128 v[176:179], v237 offset:35840
	ds_read_b128 v[180:183], v237 offset:36864
	ds_read_b128 v[184:187], v237 offset:37888
	ds_read_b128 v[188:191], v237 offset:38912
	ds_read_b128 v[192:195], v237 offset:39936
	s_mov_b32 m0, s62
	s_nop 0
	buffer_load_dwordx4 v222, s[4:7], s13 offen lds
	s_mov_b32 m0, s63
	s_nop 0
	buffer_load_dwordx4 v220, s[4:7], s39 offen lds
	s_mov_b32 m0, s66
	s_nop 0
	buffer_load_dwordx4 v222, s[4:7], s39 offen lds
	s_waitcnt vmcnt(8)
	s_waitcnt lgkmcnt(0)
	s_barrier
	s_setprio 1
	s_waitcnt lgkmcnt(0)
	v_mfma_f32_16x16x32_bf16 v[128:131], v[132:135], v[164:167], v[128:131]
	v_mfma_f32_16x16x32_bf16 v[124:127], v[140:143], v[164:167], v[124:127]
	v_mfma_f32_16x16x32_bf16 v[116:119], v[140:143], v[172:175], v[116:119]
	v_mfma_f32_16x16x32_bf16 v[120:123], v[132:135], v[172:175], v[120:123]
	v_mfma_f32_16x16x32_bf16 v[112:115], v[132:135], v[180:183], v[112:115]
	v_mfma_f32_16x16x32_bf16 v[108:111], v[140:143], v[180:183], v[108:111]
	v_mfma_f32_16x16x32_bf16 v[100:103], v[140:143], v[188:191], v[100:103]
	v_mfma_f32_16x16x32_bf16 v[104:107], v[132:135], v[188:191], v[104:107]
	v_mfma_f32_16x16x32_bf16 v[128:131], v[136:139], v[168:171], v[128:131]
	v_mfma_f32_16x16x32_bf16 v[124:127], v[144:147], v[168:171], v[124:127]
	v_mfma_f32_16x16x32_bf16 v[116:119], v[144:147], v[176:179], v[116:119]
	v_mfma_f32_16x16x32_bf16 v[120:123], v[136:139], v[176:179], v[120:123]
	v_mfma_f32_16x16x32_bf16 v[112:115], v[136:139], v[184:187], v[112:115]
	v_mfma_f32_16x16x32_bf16 v[108:111], v[144:147], v[184:187], v[108:111]
	v_mfma_f32_16x16x32_bf16 v[100:103], v[144:147], v[192:195], v[100:103]
	v_mfma_f32_16x16x32_bf16 v[104:107], v[136:139], v[192:195], v[104:107]
	s_setprio 0
	s_setprio 1
	v_mfma_f32_16x16x32_bf16 v[96:99], v[148:151], v[164:167], v[96:99]
	v_mfma_f32_16x16x32_bf16 v[92:95], v[156:159], v[164:167], v[92:95]
	v_mfma_f32_16x16x32_bf16 v[84:87], v[156:159], v[172:175], v[84:87]
	v_mfma_f32_16x16x32_bf16 v[88:91], v[148:151], v[172:175], v[88:91]
	v_mfma_f32_16x16x32_bf16 v[80:83], v[148:151], v[180:183], v[80:83]
	v_mfma_f32_16x16x32_bf16 v[76:79], v[156:159], v[180:183], v[76:79]
	v_mfma_f32_16x16x32_bf16 v[68:71], v[156:159], v[188:191], v[68:71]
	v_mfma_f32_16x16x32_bf16 v[72:75], v[148:151], v[188:191], v[72:75]
	v_mfma_f32_16x16x32_bf16 v[96:99], v[152:155], v[168:171], v[96:99]
	v_mfma_f32_16x16x32_bf16 v[92:95], v[160:163], v[168:171], v[92:95]
	v_mfma_f32_16x16x32_bf16 v[84:87], v[160:163], v[176:179], v[84:87]
	v_mfma_f32_16x16x32_bf16 v[88:91], v[152:155], v[176:179], v[88:91]
	v_mfma_f32_16x16x32_bf16 v[80:83], v[152:155], v[184:187], v[80:83]
	v_mfma_f32_16x16x32_bf16 v[76:79], v[160:163], v[184:187], v[76:79]
	v_mfma_f32_16x16x32_bf16 v[68:71], v[160:163], v[192:195], v[68:71]
	v_mfma_f32_16x16x32_bf16 v[72:75], v[152:155], v[192:195], v[72:75]
	s_setprio 0
	s_barrier
	s_mov_b32 m0, s69
	s_add_i32 s39, s12, 0x80
	ds_read_b128 v[164:167], v237 offset:49152
	ds_read_b128 v[168:171], v237 offset:50176
	ds_read_b128 v[172:175], v237 offset:51200
	ds_read_b128 v[176:179], v237 offset:52224
	ds_read_b128 v[180:183], v237 offset:53248
	ds_read_b128 v[184:187], v237 offset:54272
	ds_read_b128 v[188:191], v237 offset:55296
	ds_read_b128 v[192:195], v237 offset:56320
	buffer_load_dwordx4 v221, s[44:47], s39 offen lds
	s_mov_b32 m0, s71
	s_add_i32 s12, s12, 0x40080
	buffer_load_dwordx4 v223, s[44:47], s39 offen lds
	s_mov_b32 m0, s74
	s_addk_i32 s13, 0x80
	buffer_load_dwordx4 v221, s[44:47], s12 offen lds
	s_mov_b32 m0, s75
	s_nop 0
	buffer_load_dwordx4 v223, s[44:47], s12 offen lds
	s_mov_b32 m0, s72
	s_nop 0
	buffer_load_dwordx4 v220, s[4:7], s13 offen lds
	s_waitcnt vmcnt(7)
	s_waitcnt lgkmcnt(0)
	s_barrier
	s_setprio 1
	s_waitcnt lgkmcnt(0)
	v_mfma_f32_16x16x32_bf16 v[64:67], v[132:135], v[164:167], v[64:67]
	v_mfma_f32_16x16x32_bf16 v[60:63], v[140:143], v[164:167], v[60:63]
	v_mfma_f32_16x16x32_bf16 v[52:55], v[140:143], v[172:175], v[52:55]
	v_mfma_f32_16x16x32_bf16 v[56:59], v[132:135], v[172:175], v[56:59]
	v_mfma_f32_16x16x32_bf16 v[48:51], v[132:135], v[180:183], v[48:51]
	v_mfma_f32_16x16x32_bf16 v[44:47], v[140:143], v[180:183], v[44:47]
	v_mfma_f32_16x16x32_bf16 v[36:39], v[140:143], v[188:191], v[36:39]
	v_mfma_f32_16x16x32_bf16 v[40:43], v[132:135], v[188:191], v[40:43]
	v_mfma_f32_16x16x32_bf16 v[64:67], v[136:139], v[168:171], v[64:67]
	v_mfma_f32_16x16x32_bf16 v[60:63], v[144:147], v[168:171], v[60:63]
	v_mfma_f32_16x16x32_bf16 v[52:55], v[144:147], v[176:179], v[52:55]
	v_mfma_f32_16x16x32_bf16 v[56:59], v[136:139], v[176:179], v[56:59]
	v_mfma_f32_16x16x32_bf16 v[48:51], v[136:139], v[184:187], v[48:51]
	v_mfma_f32_16x16x32_bf16 v[44:47], v[144:147], v[184:187], v[44:47]
	v_mfma_f32_16x16x32_bf16 v[36:39], v[144:147], v[192:195], v[36:39]
	v_mfma_f32_16x16x32_bf16 v[40:43], v[136:139], v[192:195], v[40:43]
	s_setprio 0
	s_setprio 1
	v_mfma_f32_16x16x32_bf16 v[32:35], v[148:151], v[164:167], v[32:35]
	v_mfma_f32_16x16x32_bf16 v[28:31], v[156:159], v[164:167], v[28:31]
	v_mfma_f32_16x16x32_bf16 v[20:23], v[156:159], v[172:175], v[20:23]
	v_mfma_f32_16x16x32_bf16 v[24:27], v[148:151], v[172:175], v[24:27]
	v_mfma_f32_16x16x32_bf16 v[16:19], v[148:151], v[180:183], v[16:19]
	v_mfma_f32_16x16x32_bf16 v[12:15], v[156:159], v[180:183], v[12:15]
	v_mfma_f32_16x16x32_bf16 v[2:5], v[156:159], v[188:191], v[2:5]
	v_mfma_f32_16x16x32_bf16 v[6:9], v[148:151], v[188:191], v[8:11]
	v_mfma_f32_16x16x32_bf16 v[32:35], v[152:155], v[168:171], v[32:35]
	v_mfma_f32_16x16x32_bf16 v[28:31], v[160:163], v[168:171], v[28:31]
	v_mfma_f32_16x16x32_bf16 v[20:23], v[160:163], v[176:179], v[20:23]
	v_mfma_f32_16x16x32_bf16 v[24:27], v[152:155], v[176:179], v[24:27]
	v_mfma_f32_16x16x32_bf16 v[16:19], v[152:155], v[184:187], v[16:19]
	v_mfma_f32_16x16x32_bf16 v[12:15], v[160:163], v[184:187], v[12:15]
	v_mfma_f32_16x16x32_bf16 v[4:7], v[160:163], v[192:195], v[2:5]
	v_mfma_f32_16x16x32_bf16 v[8:11], v[152:155], v[192:195], v[6:9]
	s_setprio 0
	s_barrier
	s_add_i32 s38, s38, 2
	s_add_u32 s19, s19, 0x100
	s_addc_u32 s23, s23, 0
	s_cmp_gt_u32 s38, 13
	s_mov_b64 s[12:13], s[16:17]
	s_cbranch_scc0 .LBB0_1037
	s_and_b64 vcc, exec, s[14:15]
	s_cbranch_vccz .LBB0_1040
	s_barrier

; #define PG8_STAGE(bufoff, gbase, voff) do { const int so_ = (int)(unsigned)((const char*)(gbase) - base_##voff); _Pragma("unroll") for (int _i = 0; _i < 2; ++_i) \
;         __builtin_amdgcn_raw_ptr_buffer_load_lds(rs_##voff, (PG8_LAS unsigned*)(lds + (bufoff) + ldsw + _i * 8192), 16, (int)(voff)[_i], so_, 0, 0); } while (0)
; #define PG8_LDA(dst, b, h) do { _Pragma("unroll") for (int m = 0; m < 4; ++m) _Pragma("unroll") for (int k = 0; k < 2; ++k) dst[m][k] = *(const PG8_LAS bf16x8*)(lds + PG8_SA(b, h) + aoff + m * 2048 + k * 1024); } while (0)
; #define PG8_LDB(dst, b, h) do { _Pragma("unroll") for (int n = 0; n < 2; ++n) _Pragma("unroll") for (int k = 0; k < 2; ++k) dst[n][k] = *(const PG8_LAS bf16x8*)(lds + PG8_SB(b, h) + boff + n * 2048 + k * 1024); } while (0)
; #define PG8_MMA(ai, bj, At, Bt) do { __builtin_amdgcn_s_setprio(1); _Pragma("unroll") for (int m = 0; m < 4; ++m) _Pragma("unroll") for (int n = 0; n < 2; ++n) _Pragma("unroll") for (int k = 0; k < 2; ++k) \
;         acc[ai][bj][m][n] = __builtin_amdgcn_mfma_f32_16x16x32_bf16(Bt[n][k], At[m][k], acc[ai][bj][m][n], 0, 0, 0); __builtin_amdgcn_s_setprio(0); } while (0)
; #define PG8_WAIT_V(n) asm volatile("s_waitcnt vmcnt(" #n ")" ::: "memory")
; #define PG8_WAIT_L(n) asm volatile("s_waitcnt lgkmcnt(" #n ")" ::: "memory")
; #define PG8_BAR __builtin_amdgcn_s_barrier()
; #define PG8_SCHED __builtin_amdgcn_sched_barrier(0)
; template <class Epi, class Sched, bool ALIGN_EPI = false, bool SP2 = false>
; __device__ __forceinline__ void gemm_phase(PG8_LAS unsigned char* lds, const Gemm g, const Sched& S, const Epi& E, int tid_in) {
;     ...
;             PG8_LDB(B0, 0, 0); PG8_LDB(B1, 0, 1); PG8_SCHED; PG8_LDA(At, 0, 0); PG8_STAGE(PG8_SA(1, 1), a1 + hstepA, voffA);
;             PG8_WAIT_V(8); PG8_WAIT_L(0); PG8_BAR; PG8_MMA(0, 0, At, B0); PG8_MMA(0, 1, At, B1); PG8_BAR; PG8_SCHED;
;             PG8_LDA(At, 0, 1); PG8_STAGE(PG8_SB(0, 0), b2, voffB); PG8_STAGE(PG8_SB(0, 1), b2 + hstepB, voffB); PG8_STAGE(PG8_SA(0, 0), a2, voffA);
;             PG8_WAIT_V(8); PG8_WAIT_L(0); PG8_BAR; PG8_MMA(1, 0, At, B0); PG8_MMA(1, 1, At, B1); PG8_BAR; PG8_SCHED;
.LBB0_1265:
	v_add_u32_e32 v133, 0x10000, v131
	ds_read_b128 v[134:137], v133
	ds_read_b128 v[138:141], v133 offset:1024
	ds_read_b128 v[142:145], v133 offset:2048
	ds_read_b128 v[146:149], v133 offset:3072
	v_add_u32_e32 v133, 0x14000, v131
	ds_read_b128 v[150:153], v133
	ds_read_b128 v[154:157], v133 offset:1024
	ds_read_b128 v[158:161], v133 offset:2048
	ds_read_b128 v[166:169], v133 offset:3072
	s_add_i32 s42, s18, s44
	s_add_i32 s21, s14, s44
	s_add_i32 s79, s12, s44
	s_addk_i32 s42, 0xff80
	s_sub_i32 vcc_lo, s42, 0x80000
	s_cmp_eq_u32 s19, 28
	s_cselect_b32 s21, s15, s21
	s_mov_b32 m0, s75
	ds_read_b128 v[170:173], v132
	ds_read_b128 v[174:177], v132 offset:1024
	ds_read_b128 v[178:181], v132 offset:2048
	ds_read_b128 v[182:185], v132 offset:3072
	ds_read_b128 v[186:189], v132 offset:4096
	ds_read_b128 v[190:193], v132 offset:5120
	ds_read_b128 v[200:203], v132 offset:6144
	ds_read_b128 v[206:209], v132 offset:7168
	s_mov_b32 m0, s72
	s_nop 0
	buffer_load_dwordx4 v130, s[4:7], vcc_lo offen lds
	s_mov_b32 m0, s75
	s_nop 0
	buffer_load_dwordx4 v0, s[4:7], s42 offen lds
	s_mov_b32 m0, s76
	s_nop 0
	buffer_load_dwordx4 v130, s[4:7], s42 offen lds
	s_waitcnt vmcnt(8)
	s_waitcnt lgkmcnt(0)
	s_barrier
	s_setprio 1
	s_waitcnt lgkmcnt(0)
	v_mfma_f32_16x16x32_bf16 v[34:37], v[134:137], v[170:173], v[34:37]
	v_mfma_f32_16x16x32_bf16 v[18:21], v[142:145], v[170:173], v[18:21]
	v_mfma_f32_16x16x32_bf16 v[78:81], v[142:145], v[178:181], v[78:81]
	v_mfma_f32_16x16x32_bf16 v[86:89], v[134:137], v[178:181], v[86:89]
	v_mfma_f32_16x16x32_bf16 v[106:109], v[134:137], v[186:189], v[106:109]
	v_mfma_f32_16x16x32_bf16 v[102:105], v[142:145], v[186:189], v[102:105]
	v_mfma_f32_16x16x32_bf16 v[122:125], v[142:145], v[200:203], v[122:125]
	v_mfma_f32_16x16x32_bf16 v[126:129], v[134:137], v[200:203], v[126:129]
	v_mfma_f32_16x16x32_bf16 v[34:37], v[138:141], v[174:177], v[34:37]
	v_mfma_f32_16x16x32_bf16 v[18:21], v[146:149], v[174:177], v[18:21]
	v_mfma_f32_16x16x32_bf16 v[78:81], v[146:149], v[182:185], v[78:81]
	v_mfma_f32_16x16x32_bf16 v[86:89], v[138:141], v[182:185], v[86:89]
	v_mfma_f32_16x16x32_bf16 v[106:109], v[138:141], v[190:193], v[106:109]
	v_mfma_f32_16x16x32_bf16 v[102:105], v[146:149], v[190:193], v[102:105]
	v_mfma_f32_16x16x32_bf16 v[122:125], v[146:149], v[206:209], v[122:125]
	v_mfma_f32_16x16x32_bf16 v[126:129], v[138:141], v[206:209], v[126:129]
	s_setprio 0
	s_setprio 1
	v_mfma_f32_16x16x32_bf16 v[14:17], v[150:153], v[170:173], v[14:17]
	v_mfma_f32_16x16x32_bf16 v[38:41], v[158:161], v[170:173], v[38:41]
	v_mfma_f32_16x16x32_bf16 v[90:93], v[158:161], v[178:181], v[90:93]
	v_mfma_f32_16x16x32_bf16 v[74:77], v[150:153], v[178:181], v[74:77]
	v_mfma_f32_16x16x32_bf16 v[98:101], v[150:153], v[186:189], v[98:101]
	v_mfma_f32_16x16x32_bf16 v[110:113], v[158:161], v[186:189], v[110:113]
	v_mfma_f32_16x16x32_bf16 v[114:117], v[158:161], v[200:203], v[114:117]
	v_mfma_f32_16x16x32_bf16 v[118:121], v[150:153], v[200:203], v[118:121]
	v_mfma_f32_16x16x32_bf16 v[14:17], v[154:157], v[174:177], v[14:17]
	v_mfma_f32_16x16x32_bf16 v[38:41], v[166:169], v[174:177], v[38:41]
	v_mfma_f32_16x16x32_bf16 v[90:93], v[166:169], v[182:185], v[90:93]
	v_mfma_f32_16x16x32_bf16 v[74:77], v[154:157], v[182:185], v[74:77]
	v_mfma_f32_16x16x32_bf16 v[98:101], v[154:157], v[190:193], v[98:101]
	v_mfma_f32_16x16x32_bf16 v[110:113], v[166:169], v[190:193], v[110:113]
	v_mfma_f32_16x16x32_bf16 v[114:117], v[166:169], v[206:209], v[114:117]
	v_mfma_f32_16x16x32_bf16 v[118:121], v[154:157], v[206:209], v[118:121]
	s_setprio 0
	s_barrier
	s_cselect_b32 s79, s17, s79
	s_mov_b32 m0, s49
	s_mov_b32 s42, s6
	s_mov_b32 s43, s7
	s_sub_i32 s79, s79, s40
	ds_read_b128 v[170:173], v132 offset:16384
	ds_read_b128 v[174:177], v132 offset:17408
	ds_read_b128 v[178:181], v132 offset:18432
	ds_read_b128 v[182:185], v132 offset:19456
	ds_read_b128 v[186:189], v132 offset:20480
	ds_read_b128 v[190:193], v132 offset:21504
	ds_read_b128 v[200:203], v132 offset:22528
	ds_read_b128 v[206:209], v132 offset:23552
	buffer_load_dwordx4 v0, s[40:43], s79 offen lds
	s_mov_b32 m0, s60
	s_add_i32 vcc_lo, s79, 0x80000
	buffer_load_dwordx4 v130, s[40:43], s79 offen lds
	s_mov_b32 m0, s61
	s_sub_i32 s21, s21, s4
	buffer_load_dwordx4 v0, s[40:43], vcc_lo offen lds
	s_mov_b32 m0, s62
	s_nop 0
	buffer_load_dwordx4 v130, s[40:43], vcc_lo offen lds
	s_mov_b32 m0, s35
	s_nop 0
	buffer_load_dwordx4 v0, s[4:7], s21 offen lds
	s_waitcnt vmcnt(7)
	s_waitcnt lgkmcnt(0)
	s_barrier
	s_setprio 1
	s_waitcnt lgkmcnt(0)
	v_mfma_f32_16x16x32_bf16 v[50:53], v[134:137], v[170:173], v[50:53]
	v_mfma_f32_16x16x32_bf16 v[30:33], v[142:145], v[170:173], v[30:33]
	v_mfma_f32_16x16x32_bf16 v[58:61], v[142:145], v[178:181], v[58:61]
	v_mfma_f32_16x16x32_bf16 v[62:65], v[134:137], v[178:181], v[62:65]
	v_mfma_f32_16x16x32_bf16 v[94:97], v[134:137], v[186:189], v[94:97]
	v_mfma_f32_16x16x32_bf16 v[82:85], v[142:145], v[186:189], v[82:85]
	v_mfma_f32_16x16x32_bf16 v[26:29], v[142:145], v[200:203], v[26:29]
	v_mfma_f32_16x16x32_bf16 v[46:49], v[134:137], v[200:203], v[46:49]
	v_mfma_f32_16x16x32_bf16 v[50:53], v[138:141], v[174:177], v[50:53]
	v_mfma_f32_16x16x32_bf16 v[30:33], v[146:149], v[174:177], v[30:33]
	v_mfma_f32_16x16x32_bf16 v[58:61], v[146:149], v[182:185], v[58:61]
	v_mfma_f32_16x16x32_bf16 v[62:65], v[138:141], v[182:185], v[62:65]
	v_mfma_f32_16x16x32_bf16 v[94:97], v[138:141], v[190:193], v[94:97]
	v_mfma_f32_16x16x32_bf16 v[82:85], v[146:149], v[190:193], v[82:85]
	v_mfma_f32_16x16x32_bf16 v[26:29], v[146:149], v[206:209], v[26:29]
	v_mfma_f32_16x16x32_bf16 v[46:49], v[138:141], v[206:209], v[46:49]
	s_setprio 0
	s_setprio 1
	v_mfma_f32_16x16x32_bf16 v[22:25], v[150:153], v[170:173], v[22:25]
	v_mfma_f32_16x16x32_bf16 v[10:13], v[158:161], v[170:173], v[10:13]
	v_mfma_f32_16x16x32_bf16 v[66:69], v[158:161], v[178:181], v[66:69]
	v_mfma_f32_16x16x32_bf16 v[54:57], v[150:153], v[178:181], v[54:57]
	v_mfma_f32_16x16x32_bf16 v[70:73], v[150:153], v[186:189], v[70:73]
	v_mfma_f32_16x16x32_bf16 v[42:45], v[158:161], v[186:189], v[42:45]
	v_mfma_f32_16x16x32_bf16 v[2:5], v[158:161], v[200:203], v[2:5]
	v_mfma_f32_16x16x32_bf16 v[6:9], v[150:153], v[200:203], v[6:9]
	v_mfma_f32_16x16x32_bf16 v[22:25], v[154:157], v[174:177], v[22:25]
	v_mfma_f32_16x16x32_bf16 v[10:13], v[166:169], v[174:177], v[10:13]
	v_mfma_f32_16x16x32_bf16 v[66:69], v[166:169], v[182:185], v[66:69]
	v_mfma_f32_16x16x32_bf16 v[54:57], v[154:157], v[182:185], v[54:57]
	v_mfma_f32_16x16x32_bf16 v[70:73], v[154:157], v[190:193], v[70:73]
	v_mfma_f32_16x16x32_bf16 v[42:45], v[166:169], v[190:193], v[42:45]
	v_mfma_f32_16x16x32_bf16 v[2:5], v[166:169], v[206:209], v[2:5]
	v_mfma_f32_16x16x32_bf16 v[6:9], v[154:157], v[206:209], v[6:9]
	s_setprio 0
	s_barrier
; #define PG8_STAGE(bufoff, gbase, voff) do { const int so_ = (int)(unsigned)((const char*)(gbase) - base_##voff); _Pragma("unroll") for (int _i = 0; _i < 2; ++_i) \
;         __builtin_amdgcn_raw_ptr_buffer_load_lds(rs_##voff, (PG8_LAS unsigned*)(lds + (bufoff) + ldsw + _i * 8192), 16, (int)(voff)[_i], so_, 0, 0); } while (0)
; #define PG8_LDA(dst, b, h) do { _Pragma("unroll") for (int m = 0; m < 4; ++m) _Pragma("unroll") for (int k = 0; k < 2; ++k) dst[m][k] = *(const PG8_LAS bf16x8*)(lds + PG8_SA(b, h) + aoff + m * 2048 + k * 1024); } while (0)
; #define PG8_LDB(dst, b, h) do { _Pragma("unroll") for (int n = 0; n < 2; ++n) _Pragma("unroll") for (int k = 0; k < 2; ++k) dst[n][k] = *(const PG8_LAS bf16x8*)(lds + PG8_SB(b, h) + boff + n * 2048 + k * 1024); } while (0)
; #define PG8_MMA(ai, bj, At, Bt) do { __builtin_amdgcn_s_setprio(1); _Pragma("unroll") for (int m = 0; m < 4; ++m) _Pragma("unroll") for (int n = 0; n < 2; ++n) _Pragma("unroll") for (int k = 0; k < 2; ++k) \
;         acc[ai][bj][m][n] = __builtin_amdgcn_mfma_f32_16x16x32_bf16(Bt[n][k], At[m][k], acc[ai][bj][m][n], 0, 0, 0); __builtin_amdgcn_s_setprio(0); } while (0)
; #define PG8_WAIT_V(n) asm volatile("s_waitcnt vmcnt(" #n ")" ::: "memory")
; #define PG8_WAIT_L(n) asm volatile("s_waitcnt lgkmcnt(" #n ")" ::: "memory")
; #define PG8_BAR __builtin_amdgcn_s_barrier()
; #define PG8_SCHED __builtin_amdgcn_sched_barrier(0)
; template <class Epi, class Sched, bool ALIGN_EPI = false, bool SP2 = false>
; __device__ __forceinline__ void gemm_phase(PG8_LAS unsigned char* lds, const Gemm g, const Sched& S, const Epi& E, int tid_in) {
;     ...
;             PG8_LDB(B0, 1, 0); PG8_LDB(B1, 1, 1); PG8_SCHED; PG8_LDA(At, 1, 0); PG8_STAGE(PG8_SA(0, 1), a2 + hstepA, voffA);
;             PG8_WAIT_V(8); PG8_WAIT_L(0); PG8_BAR; PG8_MMA(0, 0, At, B0); PG8_MMA(0, 1, At, B1); PG8_BAR; PG8_SCHED;
;             PG8_LDA(At, 1, 1); PG8_STAGE(PG8_SB(1, 0), b3, voffB); PG8_STAGE(PG8_SB(1, 1), b3 + hstepB, voffB); PG8_STAGE(PG8_SA(1, 0), a3, voffA);
;             PG8_WAIT_V(8); PG8_WAIT_L(0); PG8_BAR; PG8_MMA(1, 0, At, B0); PG8_MMA(1, 1, At, B1); PG8_BAR; PG8_SCHED;
	v_add_u32_e32 v133, 0x18000, v131
	ds_read_b128 v[134:137], v133
	ds_read_b128 v[138:141], v133 offset:1024
	ds_read_b128 v[142:145], v133 offset:2048
	ds_read_b128 v[146:149], v133 offset:3072
	v_add_u32_e32 v133, 0x1c000, v131
	ds_read_b128 v[150:153], v133
	ds_read_b128 v[154:157], v133 offset:1024
	ds_read_b128 v[158:161], v133 offset:2048
	ds_read_b128 v[166:169], v133 offset:3072
	s_add_i32 vcc_lo, s21, 0x80000
	s_mov_b32 m0, s66
	ds_read_b128 v[170:173], v132 offset:32768
	ds_read_b128 v[174:177], v132 offset:33792
	ds_read_b128 v[178:181], v132 offset:34816
	ds_read_b128 v[182:185], v132 offset:35840
	ds_read_b128 v[186:189], v132 offset:36864
	ds_read_b128 v[190:193], v132 offset:37888
	ds_read_b128 v[200:203], v132 offset:38912
	ds_read_b128 v[206:209], v132 offset:39936
	s_mov_b32 m0, s63
	s_nop 0
	buffer_load_dwordx4 v130, s[4:7], s21 offen lds
	s_mov_b32 m0, s66
	s_nop 0
	buffer_load_dwordx4 v0, s[4:7], vcc_lo offen lds
	s_mov_b32 m0, s67
	s_nop 0
	buffer_load_dwordx4 v130, s[4:7], vcc_lo offen lds
	s_waitcnt vmcnt(8)
	s_waitcnt lgkmcnt(0)
	s_barrier
	s_setprio 1
	s_waitcnt lgkmcnt(0)
	v_mfma_f32_16x16x32_bf16 v[34:37], v[134:137], v[170:173], v[34:37]
	v_mfma_f32_16x16x32_bf16 v[18:21], v[142:145], v[170:173], v[18:21]
	v_mfma_f32_16x16x32_bf16 v[78:81], v[142:145], v[178:181], v[78:81]
	v_mfma_f32_16x16x32_bf16 v[86:89], v[134:137], v[178:181], v[86:89]
	v_mfma_f32_16x16x32_bf16 v[106:109], v[134:137], v[186:189], v[106:109]
	v_mfma_f32_16x16x32_bf16 v[102:105], v[142:145], v[186:189], v[102:105]
	v_mfma_f32_16x16x32_bf16 v[122:125], v[142:145], v[200:203], v[122:125]
	v_mfma_f32_16x16x32_bf16 v[126:129], v[134:137], v[200:203], v[126:129]
	v_mfma_f32_16x16x32_bf16 v[34:37], v[138:141], v[174:177], v[34:37]
	v_mfma_f32_16x16x32_bf16 v[18:21], v[146:149], v[174:177], v[18:21]
	v_mfma_f32_16x16x32_bf16 v[78:81], v[146:149], v[182:185], v[78:81]
	v_mfma_f32_16x16x32_bf16 v[86:89], v[138:141], v[182:185], v[86:89]
	v_mfma_f32_16x16x32_bf16 v[106:109], v[138:141], v[190:193], v[106:109]
	v_mfma_f32_16x16x32_bf16 v[102:105], v[146:149], v[190:193], v[102:105]
	v_mfma_f32_16x16x32_bf16 v[122:125], v[146:149], v[206:209], v[122:125]
	v_mfma_f32_16x16x32_bf16 v[126:129], v[138:141], v[206:209], v[126:129]
	s_setprio 0
	s_setprio 1
	v_mfma_f32_16x16x32_bf16 v[14:17], v[150:153], v[170:173], v[14:17]
	v_mfma_f32_16x16x32_bf16 v[38:41], v[158:161], v[170:173], v[38:41]
	v_mfma_f32_16x16x32_bf16 v[90:93], v[158:161], v[178:181], v[90:93]
	v_mfma_f32_16x16x32_bf16 v[74:77], v[150:153], v[178:181], v[74:77]
	v_mfma_f32_16x16x32_bf16 v[98:101], v[150:153], v[186:189], v[98:101]
	v_mfma_f32_16x16x32_bf16 v[110:113], v[158:161], v[186:189], v[110:113]
	v_mfma_f32_16x16x32_bf16 v[114:117], v[158:161], v[200:203], v[114:117]
	v_mfma_f32_16x16x32_bf16 v[118:121], v[150:153], v[200:203], v[118:121]
	v_mfma_f32_16x16x32_bf16 v[14:17], v[154:157], v[174:177], v[14:17]
	v_mfma_f32_16x16x32_bf16 v[38:41], v[166:169], v[174:177], v[38:41]
	v_mfma_f32_16x16x32_bf16 v[90:93], v[166:169], v[182:185], v[90:93]
	v_mfma_f32_16x16x32_bf16 v[74:77], v[154:157], v[182:185], v[74:77]
	v_mfma_f32_16x16x32_bf16 v[98:101], v[154:157], v[190:193], v[98:101]
	v_mfma_f32_16x16x32_bf16 v[110:113], v[166:169], v[190:193], v[110:113]
	v_mfma_f32_16x16x32_bf16 v[114:117], v[166:169], v[206:209], v[114:117]
	v_mfma_f32_16x16x32_bf16 v[118:121], v[154:157], v[206:209], v[118:121]
	s_setprio 0
	s_barrier
	s_mov_b32 m0, s68
	s_add_i32 vcc_lo, s79, 0x80
	ds_read_b128 v[170:173], v132 offset:49152
	ds_read_b128 v[174:177], v132 offset:50176
	ds_read_b128 v[178:181], v132 offset:51200
	ds_read_b128 v[182:185], v132 offset:52224
	ds_read_b128 v[186:189], v132 offset:53248
	ds_read_b128 v[190:193], v132 offset:54272
	ds_read_b128 v[200:203], v132 offset:55296
	ds_read_b128 v[206:209], v132 offset:56320
	buffer_load_dwordx4 v0, s[40:43], vcc_lo offen lds
	s_mov_b32 m0, s69
	s_add_i32 s79, s79, 0x80080
	buffer_load_dwordx4 v130, s[40:43], vcc_lo offen lds
	s_mov_b32 m0, s73
	s_addk_i32 s21, 0x80
	buffer_load_dwordx4 v0, s[40:43], s79 offen lds
	s_mov_b32 m0, s74
	s_nop 0
	buffer_load_dwordx4 v130, s[40:43], s79 offen lds
	s_mov_b32 m0, s71
	s_nop 0
	buffer_load_dwordx4 v0, s[4:7], s21 offen lds
	s_waitcnt vmcnt(7)
	s_waitcnt lgkmcnt(0)
	s_barrier
; #define PG8_MMA(ai, bj, At, Bt) do { __builtin_amdgcn_s_setprio(1); _Pragma("unroll") for (int m = 0; m < 4; ++m) _Pragma("unroll") for (int n = 0; n < 2; ++n) _Pragma("unroll") for (int k = 0; k < 2; ++k) \
;         acc[ai][bj][m][n] = __builtin_amdgcn_mfma_f32_16x16x32_bf16(Bt[n][k], At[m][k], acc[ai][bj][m][n], 0, 0, 0); __builtin_amdgcn_s_setprio(0); } while (0)
; #define PG8_WAIT_V(n) asm volatile("s_waitcnt vmcnt(" #n ")" ::: "memory")
; #define PG8_WAIT_L(n) asm volatile("s_waitcnt lgkmcnt(" #n ")" ::: "memory")
; #define PG8_BAR __builtin_amdgcn_s_barrier()
; #define PG8_SCHED __builtin_amdgcn_sched_barrier(0)
; template <class Epi, class Sched, bool ALIGN_EPI = false, bool SP2 = false>
; __device__ __forceinline__ void gemm_phase(PG8_LAS unsigned char* lds, const Gemm g, const Sched& S, const Epi& E, int tid_in) {
;     ...
;             PG8_WAIT_V(8); PG8_WAIT_L(0); PG8_BAR; PG8_MMA(1, 0, At, B0); PG8_MMA(1, 1, At, B1); PG8_BAR; PG8_SCHED;
;     ...
;         if (zero_acc) {
; #pragma unroll
;         for (int a = 0; a < 2; ++a)
; #pragma unroll
;             for (int b = 0; b < 2; ++b)
; #pragma unroll
;                 for (int m = 0; m < 4; ++m)
; #pragma unroll
;                     for (int n = 0; n < 2; ++n) acc[a][b][m][n] = (f32x4){0.f, 0.f, 0.f, 0.f};
;         }
	s_setprio 1
	s_waitcnt lgkmcnt(0)
	v_mfma_f32_16x16x32_bf16 v[50:53], v[134:137], v[170:173], v[50:53]
	v_mfma_f32_16x16x32_bf16 v[30:33], v[142:145], v[170:173], v[30:33]
	v_mfma_f32_16x16x32_bf16 v[58:61], v[142:145], v[178:181], v[58:61]
	v_mfma_f32_16x16x32_bf16 v[62:65], v[134:137], v[178:181], v[62:65]
	v_mfma_f32_16x16x32_bf16 v[94:97], v[134:137], v[186:189], v[94:97]
	v_mfma_f32_16x16x32_bf16 v[82:85], v[142:145], v[186:189], v[82:85]
	v_mfma_f32_16x16x32_bf16 v[26:29], v[142:145], v[200:203], v[26:29]
	v_mfma_f32_16x16x32_bf16 v[46:49], v[134:137], v[200:203], v[46:49]
	v_mfma_f32_16x16x32_bf16 v[50:53], v[138:141], v[174:177], v[50:53]
	v_mfma_f32_16x16x32_bf16 v[30:33], v[146:149], v[174:177], v[30:33]
	v_mfma_f32_16x16x32_bf16 v[58:61], v[146:149], v[182:185], v[58:61]
	v_mfma_f32_16x16x32_bf16 v[62:65], v[138:141], v[182:185], v[62:65]
	v_mfma_f32_16x16x32_bf16 v[94:97], v[138:141], v[190:193], v[94:97]
	v_mfma_f32_16x16x32_bf16 v[82:85], v[146:149], v[190:193], v[82:85]
	v_mfma_f32_16x16x32_bf16 v[26:29], v[146:149], v[206:209], v[26:29]
	v_mfma_f32_16x16x32_bf16 v[46:49], v[138:141], v[206:209], v[46:49]
	s_setprio 0
	s_setprio 1
	v_mfma_f32_16x16x32_bf16 v[22:25], v[150:153], v[170:173], v[22:25]
	v_mfma_f32_16x16x32_bf16 v[10:13], v[158:161], v[170:173], v[10:13]
	v_mfma_f32_16x16x32_bf16 v[66:69], v[158:161], v[178:181], v[66:69]
	v_mfma_f32_16x16x32_bf16 v[54:57], v[150:153], v[178:181], v[54:57]
	v_mfma_f32_16x16x32_bf16 v[70:73], v[150:153], v[186:189], v[70:73]
	v_mfma_f32_16x16x32_bf16 v[42:45], v[158:161], v[186:189], v[42:45]
	v_mfma_f32_16x16x32_bf16 v[2:5], v[158:161], v[200:203], v[2:5]
	v_mfma_f32_16x16x32_bf16 v[6:9], v[150:153], v[200:203], v[6:9]
	v_mfma_f32_16x16x32_bf16 v[22:25], v[154:157], v[174:177], v[22:25]
	v_mfma_f32_16x16x32_bf16 v[10:13], v[166:169], v[174:177], v[10:13]
	v_mfma_f32_16x16x32_bf16 v[66:69], v[166:169], v[182:185], v[66:69]
	v_mfma_f32_16x16x32_bf16 v[54:57], v[154:157], v[182:185], v[54:57]
	v_mfma_f32_16x16x32_bf16 v[70:73], v[154:157], v[190:193], v[70:73]
	v_mfma_f32_16x16x32_bf16 v[42:45], v[166:169], v[190:193], v[42:45]
	v_mfma_f32_16x16x32_bf16 v[2:5], v[166:169], v[206:209], v[2:5]
	v_mfma_f32_16x16x32_bf16 v[6:9], v[154:157], v[206:209], v[6:9]
	s_setprio 0
	s_barrier
	s_add_i32 s19, s19, 2
	s_add_u32 s44, s44, 0x100
	s_addc_u32 s45, s45, 0
	s_cmp_gt_u32 s19, 29
	s_cbranch_scc0 .LBB0_1265
	s_andn2_b64 vcc, exec, s[38:39]
	s_cbranch_vccnz .LBB0_1257
	v_mov_b32_e32 v2, 0
	s_mov_b64 s[12:13], s[24:25]
	s_mov_b32 s10, s16
	s_mov_b32 s48, s20
	s_mov_b64 s[14:15], s[22:23]
	s_mov_b32 s13, s78
	v_mov_b32_e32 v3, v2
	v_mov_b32_e32 v4, v2
	v_mov_b32_e32 v5, v2
	v_mov_b32_e32 v6, v2
	v_mov_b32_e32 v7, v2
	v_mov_b32_e32 v8, v2
	v_mov_b32_e32 v9, v2
	v_mov_b32_e32 v42, v2
	v_mov_b32_e32 v43, v2
	v_mov_b32_e32 v44, v2
	v_mov_b32_e32 v45, v2
	v_mov_b32_e32 v70, v2
	v_mov_b32_e32 v71, v2
	v_mov_b32_e32 v72, v2
	v_mov_b32_e32 v73, v2
	v_mov_b32_e32 v66, v2
	v_mov_b32_e32 v67, v2
	v_mov_b32_e32 v68, v2
	v_mov_b32_e32 v69, v2
	v_mov_b32_e32 v54, v2
	v_mov_b32_e32 v55, v2
	v_mov_b32_e32 v56, v2
	v_mov_b32_e32 v57, v2
	v_mov_b32_e32 v10, v2
	v_mov_b32_e32 v11, v2
	v_mov_b32_e32 v12, v2
	v_mov_b32_e32 v13, v2
	v_mov_b32_e32 v22, v2
	v_mov_b32_e32 v23, v2
	v_mov_b32_e32 v24, v2
	v_mov_b32_e32 v25, v2
	v_mov_b32_e32 v26, v2
	v_mov_b32_e32 v27, v2
	v_mov_b32_e32 v28, v2
	v_mov_b32_e32 v29, v2
	v_mov_b32_e32 v46, v2
	v_mov_b32_e32 v47, v2
	v_mov_b32_e32 v48, v2
	v_mov_b32_e32 v49, v2
	v_mov_b32_e32 v82, v2
	v_mov_b32_e32 v83, v2
	v_mov_b32_e32 v84, v2
	v_mov_b32_e32 v85, v2
	v_mov_b32_e32 v94, v2
	v_mov_b32_e32 v95, v2
	v_mov_b32_e32 v96, v2
	v_mov_b32_e32 v97, v2
	v_mov_b32_e32 v58, v2
	v_mov_b32_e32 v59, v2
	v_mov_b32_e32 v60, v2
	v_mov_b32_e32 v61, v2
	v_mov_b32_e32 v62, v2
	v_mov_b32_e32 v63, v2
	v_mov_b32_e32 v64, v2
	v_mov_b32_e32 v65, v2
	v_mov_b32_e32 v30, v2
	v_mov_b32_e32 v31, v2
	v_mov_b32_e32 v32, v2
	v_mov_b32_e32 v33, v2
	v_mov_b32_e32 v50, v2
	v_mov_b32_e32 v51, v2
	v_mov_b32_e32 v52, v2
	v_mov_b32_e32 v53, v2
	v_mov_b32_e32 v114, v2
	v_mov_b32_e32 v115, v2
	v_mov_b32_e32 v116, v2
	v_mov_b32_e32 v117, v2
	v_mov_b32_e32 v118, v2
	v_mov_b32_e32 v119, v2
	v_mov_b32_e32 v120, v2
	v_mov_b32_e32 v121, v2
	v_mov_b32_e32 v110, v2
	v_mov_b32_e32 v111, v2
	v_mov_b32_e32 v112, v2
	v_mov_b32_e32 v113, v2
	v_mov_b32_e32 v98, v2
	v_mov_b32_e32 v99, v2
	v_mov_b32_e32 v100, v2
	v_mov_b32_e32 v101, v2
	v_mov_b32_e32 v90, v2
	v_mov_b32_e32 v91, v2
	v_mov_b32_e32 v92, v2
	v_mov_b32_e32 v93, v2
	v_mov_b32_e32 v74, v2
	v_mov_b32_e32 v75, v2
	v_mov_b32_e32 v76, v2
	v_mov_b32_e32 v77, v2
	v_mov_b32_e32 v38, v2
	v_mov_b32_e32 v39, v2
	v_mov_b32_e32 v40, v2
	v_mov_b32_e32 v41, v2
	v_mov_b32_e32 v14, v2
	v_mov_b32_e32 v15, v2
	v_mov_b32_e32 v16, v2
	v_mov_b32_e32 v17, v2
	v_mov_b32_e32 v122, v2
	v_mov_b32_e32 v123, v2
	v_mov_b32_e32 v124, v2
	v_mov_b32_e32 v125, v2
	v_mov_b32_e32 v126, v2
	v_mov_b32_e32 v127, v2
	v_mov_b32_e32 v128, v2
	v_mov_b32_e32 v129, v2
	v_mov_b32_e32 v102, v2
	v_mov_b32_e32 v103, v2
	v_mov_b32_e32 v104, v2
	v_mov_b32_e32 v105, v2
	v_mov_b32_e32 v106, v2
	v_mov_b32_e32 v107, v2
	v_mov_b32_e32 v108, v2
	v_mov_b32_e32 v109, v2
	v_mov_b32_e32 v78, v2
	v_mov_b32_e32 v79, v2
	v_mov_b32_e32 v80, v2
	v_mov_b32_e32 v81, v2
	v_mov_b32_e32 v86, v2
	v_mov_b32_e32 v87, v2
	v_mov_b32_e32 v88, v2
	v_mov_b32_e32 v89, v2
	v_mov_b32_e32 v18, v2
	v_mov_b32_e32 v19, v2
	v_mov_b32_e32 v20, v2
	v_mov_b32_e32 v21, v2
	v_mov_b32_e32 v34, v2
	v_mov_b32_e32 v35, v2
	v_mov_b32_e32 v36, v2
	v_mov_b32_e32 v37, v2
	s_branch .LBB0_1257

; #define PG8_STAGE(bufoff, gbase, voff) do { const int so_ = (int)(unsigned)((const char*)(gbase) - base_##voff); _Pragma("unroll") for (int _i = 0; _i < 2; ++_i) \
;         __builtin_amdgcn_raw_ptr_buffer_load_lds(rs_##voff, (PG8_LAS unsigned*)(lds + (bufoff) + ldsw + _i * 8192), 16, (int)(voff)[_i], so_, 0, 0); } while (0)
; #define PG8_LDA(dst, b, h) do { _Pragma("unroll") for (int m = 0; m < 4; ++m) _Pragma("unroll") for (int k = 0; k < 2; ++k) dst[m][k] = *(const PG8_LAS bf16x8*)(lds + PG8_SA(b, h) + aoff + m * 2048 + k * 1024); } while (0)
; #define PG8_LDB(dst, b, h) do { _Pragma("unroll") for (int n = 0; n < 2; ++n) _Pragma("unroll") for (int k = 0; k < 2; ++k) dst[n][k] = *(const PG8_LAS bf16x8*)(lds + PG8_SB(b, h) + boff + n * 2048 + k * 1024); } while (0)
; #define PG8_MMA(ai, bj, At, Bt) do { __builtin_amdgcn_s_setprio(1); _Pragma("unroll") for (int m = 0; m < 4; ++m) _Pragma("unroll") for (int n = 0; n < 2; ++n) _Pragma("unroll") for (int k = 0; k < 2; ++k) \
;         acc[ai][bj][m][n] = __builtin_amdgcn_mfma_f32_16x16x32_bf16(Bt[n][k], At[m][k], acc[ai][bj][m][n], 0, 0, 0); __builtin_amdgcn_s_setprio(0); } while (0)
; #define PG8_WAIT_V(n) asm volatile("s_waitcnt vmcnt(" #n ")" ::: "memory")
; #define PG8_WAIT_L(n) asm volatile("s_waitcnt lgkmcnt(" #n ")" ::: "memory")
; #define PG8_BAR __builtin_amdgcn_s_barrier()
; #define PG8_SCHED __builtin_amdgcn_sched_barrier(0)
; template <class Epi, class Sched, bool ALIGN_EPI = false, bool SP2 = false>
; __device__ __forceinline__ void gemm_phase(PG8_LAS unsigned char* lds, const Gemm g, const Sched& S, const Epi& E, int tid_in) {
;     ...
;             PG8_LDB(B0, 0, 0); PG8_LDB(B1, 0, 1); PG8_SCHED; PG8_LDA(At, 0, 0); PG8_STAGE(PG8_SA(1, 1), a1 + hstepA, voffA);
;             PG8_WAIT_V(8); PG8_WAIT_L(0); PG8_BAR; PG8_MMA(0, 0, At, B0); PG8_MMA(0, 1, At, B1); PG8_BAR; PG8_SCHED;
;             PG8_LDA(At, 0, 1); PG8_STAGE(PG8_SB(0, 0), b2, voffB); PG8_STAGE(PG8_SB(0, 1), b2 + hstepB, voffB); PG8_STAGE(PG8_SA(0, 0), a2, voffA);
;             PG8_WAIT_V(8); PG8_WAIT_L(0); PG8_BAR; PG8_MMA(1, 0, At, B0); PG8_MMA(1, 1, At, B1); PG8_BAR; PG8_SCHED;
.LBB0_1514:
	v_add_u32_e32 v141, 0x10000, v139
	ds_read_b128 v[130:133], v141
	ds_read_b128 v[142:145], v141 offset:1024
	ds_read_b128 v[146:149], v141 offset:2048
	ds_read_b128 v[150:153], v141 offset:3072
	v_add_u32_e32 v141, 0x14000, v139
	ds_read_b128 v[154:157], v141
	ds_read_b128 v[158:161], v141 offset:1024
	ds_read_b128 v[162:165], v141 offset:2048
	ds_read_b128 v[166:169], v141 offset:3072
	s_add_u32 s38, s16, 0x100
	s_addc_u32 s39, s17, 0
	s_sub_i32 s16, s16, s4
	s_add_i32 s16, s16, 0x80080
	s_sub_i32 s74, s16, 0x80000
	s_cmp_eq_u32 s73, 28
	s_cselect_b32 s17, s18, s38
	s_mov_b32 m0, s67
	ds_read_b128 v[170:173], v140
	ds_read_b128 v[174:177], v140 offset:1024
	ds_read_b128 v[178:181], v140 offset:2048
	ds_read_b128 v[182:185], v140 offset:3072
	ds_read_b128 v[186:189], v140 offset:4096
	ds_read_b128 v[190:193], v140 offset:5120
	ds_read_b128 v[200:203], v140 offset:6144
	ds_read_b128 v[206:209], v140 offset:7168
	s_mov_b32 m0, s62
	s_nop 0
	buffer_load_dwordx4 v135, s[4:7], s74 offen lds
	s_mov_b32 m0, s67
	s_nop 0
	buffer_load_dwordx4 v0, s[4:7], s16 offen lds
	s_mov_b32 m0, s68
	s_nop 0
	buffer_load_dwordx4 v135, s[4:7], s16 offen lds
	s_waitcnt vmcnt(8)
	s_waitcnt lgkmcnt(0)
	s_barrier
	s_setprio 1
	s_waitcnt lgkmcnt(0)
	v_mfma_f32_16x16x32_bf16 v[126:129], v[130:133], v[170:173], v[126:129]
	v_mfma_f32_16x16x32_bf16 v[122:125], v[146:149], v[170:173], v[122:125]
	v_mfma_f32_16x16x32_bf16 v[106:109], v[146:149], v[178:181], v[106:109]
	v_mfma_f32_16x16x32_bf16 v[110:113], v[130:133], v[178:181], v[110:113]
	v_mfma_f32_16x16x32_bf16 v[94:97], v[130:133], v[186:189], v[94:97]
	v_mfma_f32_16x16x32_bf16 v[90:93], v[146:149], v[186:189], v[90:93]
	v_mfma_f32_16x16x32_bf16 v[74:77], v[146:149], v[200:203], v[74:77]
	v_mfma_f32_16x16x32_bf16 v[78:81], v[130:133], v[200:203], v[78:81]
	v_mfma_f32_16x16x32_bf16 v[126:129], v[142:145], v[174:177], v[126:129]
	v_mfma_f32_16x16x32_bf16 v[122:125], v[150:153], v[174:177], v[122:125]
	v_mfma_f32_16x16x32_bf16 v[106:109], v[150:153], v[182:185], v[106:109]
	v_mfma_f32_16x16x32_bf16 v[110:113], v[142:145], v[182:185], v[110:113]
	v_mfma_f32_16x16x32_bf16 v[94:97], v[142:145], v[190:193], v[94:97]
	v_mfma_f32_16x16x32_bf16 v[90:93], v[150:153], v[190:193], v[90:93]
	v_mfma_f32_16x16x32_bf16 v[74:77], v[150:153], v[206:209], v[74:77]
	v_mfma_f32_16x16x32_bf16 v[78:81], v[142:145], v[206:209], v[78:81]
	s_setprio 0
	s_setprio 1
	v_mfma_f32_16x16x32_bf16 v[118:121], v[154:157], v[170:173], v[118:121]
	v_mfma_f32_16x16x32_bf16 v[114:117], v[162:165], v[170:173], v[114:117]
	v_mfma_f32_16x16x32_bf16 v[98:101], v[162:165], v[178:181], v[98:101]
	v_mfma_f32_16x16x32_bf16 v[102:105], v[154:157], v[178:181], v[102:105]
	v_mfma_f32_16x16x32_bf16 v[86:89], v[154:157], v[186:189], v[86:89]
	v_mfma_f32_16x16x32_bf16 v[82:85], v[162:165], v[186:189], v[82:85]
	v_mfma_f32_16x16x32_bf16 v[66:69], v[162:165], v[200:203], v[66:69]
	v_mfma_f32_16x16x32_bf16 v[70:73], v[154:157], v[200:203], v[70:73]
	v_mfma_f32_16x16x32_bf16 v[118:121], v[158:161], v[174:177], v[118:121]
	v_mfma_f32_16x16x32_bf16 v[114:117], v[166:169], v[174:177], v[114:117]
	v_mfma_f32_16x16x32_bf16 v[98:101], v[166:169], v[182:185], v[98:101]
	v_mfma_f32_16x16x32_bf16 v[102:105], v[158:161], v[182:185], v[102:105]
	v_mfma_f32_16x16x32_bf16 v[86:89], v[158:161], v[190:193], v[86:89]
	v_mfma_f32_16x16x32_bf16 v[82:85], v[166:169], v[190:193], v[82:85]
	v_mfma_f32_16x16x32_bf16 v[66:69], v[166:169], v[206:209], v[66:69]
	v_mfma_f32_16x16x32_bf16 v[70:73], v[158:161], v[206:209], v[70:73]
	s_setprio 0
	s_barrier
	s_cselect_b32 s16, s15, s19
	s_mov_b32 m0, s35
	s_mov_b32 s42, s6
	s_mov_b32 s43, s7
	s_sub_i32 s16, s16, s40
	ds_read_b128 v[170:173], v140 offset:16384
	ds_read_b128 v[174:177], v140 offset:17408
	ds_read_b128 v[178:181], v140 offset:18432
	ds_read_b128 v[182:185], v140 offset:19456
	ds_read_b128 v[186:189], v140 offset:20480
	ds_read_b128 v[190:193], v140 offset:21504
	ds_read_b128 v[200:203], v140 offset:22528
	ds_read_b128 v[206:209], v140 offset:23552
	buffer_load_dwordx4 v134, s[40:43], s16 offen lds
	s_mov_b32 m0, s44
	s_add_i32 s74, s16, 0x80000
	buffer_load_dwordx4 v136, s[40:43], s16 offen lds
	s_mov_b32 m0, s45
	s_sub_i32 s17, s17, s4
	buffer_load_dwordx4 v134, s[40:43], s74 offen lds
	s_mov_b32 m0, s46
	s_nop 0
	buffer_load_dwordx4 v136, s[40:43], s74 offen lds
	s_mov_b32 m0, s34
	s_nop 0
	buffer_load_dwordx4 v0, s[4:7], s17 offen lds
	s_waitcnt vmcnt(7)
	s_waitcnt lgkmcnt(0)
	s_barrier
	s_setprio 1
	s_waitcnt lgkmcnt(0)
	v_mfma_f32_16x16x32_bf16 v[62:65], v[130:133], v[170:173], v[62:65]
	v_mfma_f32_16x16x32_bf16 v[58:61], v[146:149], v[170:173], v[58:61]
	v_mfma_f32_16x16x32_bf16 v[42:45], v[146:149], v[178:181], v[42:45]
	v_mfma_f32_16x16x32_bf16 v[46:49], v[130:133], v[178:181], v[46:49]
	v_mfma_f32_16x16x32_bf16 v[30:33], v[130:133], v[186:189], v[30:33]
	v_mfma_f32_16x16x32_bf16 v[26:29], v[146:149], v[186:189], v[26:29]
	v_mfma_f32_16x16x32_bf16 v[10:13], v[146:149], v[200:203], v[10:13]
	v_mfma_f32_16x16x32_bf16 v[14:17], v[130:133], v[200:203], v[14:17]
	v_mfma_f32_16x16x32_bf16 v[62:65], v[142:145], v[174:177], v[62:65]
	v_mfma_f32_16x16x32_bf16 v[58:61], v[150:153], v[174:177], v[58:61]
	v_mfma_f32_16x16x32_bf16 v[42:45], v[150:153], v[182:185], v[42:45]
	v_mfma_f32_16x16x32_bf16 v[46:49], v[142:145], v[182:185], v[46:49]
	v_mfma_f32_16x16x32_bf16 v[30:33], v[142:145], v[190:193], v[30:33]
	v_mfma_f32_16x16x32_bf16 v[26:29], v[150:153], v[190:193], v[26:29]
	v_mfma_f32_16x16x32_bf16 v[10:13], v[150:153], v[206:209], v[10:13]
	v_mfma_f32_16x16x32_bf16 v[14:17], v[142:145], v[206:209], v[14:17]
	s_setprio 0
	s_setprio 1
	v_mfma_f32_16x16x32_bf16 v[54:57], v[154:157], v[170:173], v[54:57]
	v_mfma_f32_16x16x32_bf16 v[50:53], v[162:165], v[170:173], v[50:53]
	v_mfma_f32_16x16x32_bf16 v[34:37], v[162:165], v[178:181], v[34:37]
	v_mfma_f32_16x16x32_bf16 v[38:41], v[154:157], v[178:181], v[38:41]
	v_mfma_f32_16x16x32_bf16 v[22:25], v[154:157], v[186:189], v[22:25]
	v_mfma_f32_16x16x32_bf16 v[18:21], v[162:165], v[186:189], v[18:21]
	v_mfma_f32_16x16x32_bf16 v[2:5], v[162:165], v[200:203], v[2:5]
	v_mfma_f32_16x16x32_bf16 v[6:9], v[154:157], v[200:203], v[6:9]
	v_mfma_f32_16x16x32_bf16 v[54:57], v[158:161], v[174:177], v[54:57]
	v_mfma_f32_16x16x32_bf16 v[50:53], v[166:169], v[174:177], v[50:53]
	v_mfma_f32_16x16x32_bf16 v[34:37], v[166:169], v[182:185], v[34:37]
	v_mfma_f32_16x16x32_bf16 v[38:41], v[158:161], v[182:185], v[38:41]
	v_mfma_f32_16x16x32_bf16 v[22:25], v[158:161], v[190:193], v[22:25]
	v_mfma_f32_16x16x32_bf16 v[18:21], v[166:169], v[190:193], v[18:21]
	v_mfma_f32_16x16x32_bf16 v[2:5], v[166:169], v[206:209], v[2:5]
	v_mfma_f32_16x16x32_bf16 v[6:9], v[158:161], v[206:209], v[6:9]
	s_setprio 0
	s_barrier
; #define PG8_STAGE(bufoff, gbase, voff) do { const int so_ = (int)(unsigned)((const char*)(gbase) - base_##voff); _Pragma("unroll") for (int _i = 0; _i < 2; ++_i) \
;         __builtin_amdgcn_raw_ptr_buffer_load_lds(rs_##voff, (PG8_LAS unsigned*)(lds + (bufoff) + ldsw + _i * 8192), 16, (int)(voff)[_i], so_, 0, 0); } while (0)
; #define PG8_LDA(dst, b, h) do { _Pragma("unroll") for (int m = 0; m < 4; ++m) _Pragma("unroll") for (int k = 0; k < 2; ++k) dst[m][k] = *(const PG8_LAS bf16x8*)(lds + PG8_SA(b, h) + aoff + m * 2048 + k * 1024); } while (0)
; #define PG8_LDB(dst, b, h) do { _Pragma("unroll") for (int n = 0; n < 2; ++n) _Pragma("unroll") for (int k = 0; k < 2; ++k) dst[n][k] = *(const PG8_LAS bf16x8*)(lds + PG8_SB(b, h) + boff + n * 2048 + k * 1024); } while (0)
; #define PG8_MMA(ai, bj, At, Bt) do { __builtin_amdgcn_s_setprio(1); _Pragma("unroll") for (int m = 0; m < 4; ++m) _Pragma("unroll") for (int n = 0; n < 2; ++n) _Pragma("unroll") for (int k = 0; k < 2; ++k) \
;         acc[ai][bj][m][n] = __builtin_amdgcn_mfma_f32_16x16x32_bf16(Bt[n][k], At[m][k], acc[ai][bj][m][n], 0, 0, 0); __builtin_amdgcn_s_setprio(0); } while (0)
; #define PG8_WAIT_V(n) asm volatile("s_waitcnt vmcnt(" #n ")" ::: "memory")
; #define PG8_WAIT_L(n) asm volatile("s_waitcnt lgkmcnt(" #n ")" ::: "memory")
; #define PG8_BAR __builtin_amdgcn_s_barrier()
; #define PG8_SCHED __builtin_amdgcn_sched_barrier(0)
; template <class Epi, class Sched, bool ALIGN_EPI = false, bool SP2 = false>
; __device__ __forceinline__ void gemm_phase(PG8_LAS unsigned char* lds, const Gemm g, const Sched& S, const Epi& E, int tid_in) {
;     ...
;             PG8_LDB(B0, 1, 0); PG8_LDB(B1, 1, 1); PG8_SCHED; PG8_LDA(At, 1, 0); PG8_STAGE(PG8_SA(0, 1), a2 + hstepA, voffA);
;             PG8_WAIT_V(8); PG8_WAIT_L(0); PG8_BAR; PG8_MMA(0, 0, At, B0); PG8_MMA(0, 1, At, B1); PG8_BAR; PG8_SCHED;
;             PG8_LDA(At, 1, 1); PG8_STAGE(PG8_SB(1, 0), b3, voffB); PG8_STAGE(PG8_SB(1, 1), b3 + hstepB, voffB); PG8_STAGE(PG8_SA(1, 0), a3, voffA);
;             PG8_WAIT_V(8); PG8_WAIT_L(0); PG8_BAR; PG8_MMA(1, 0, At, B0); PG8_MMA(1, 1, At, B1); PG8_BAR; PG8_SCHED;
	v_add_u32_e32 v141, 0x18000, v139
	ds_read_b128 v[130:133], v141
	ds_read_b128 v[142:145], v141 offset:1024
	ds_read_b128 v[146:149], v141 offset:2048
	ds_read_b128 v[150:153], v141 offset:3072
	v_add_u32_e32 v141, 0x1c000, v139
	ds_read_b128 v[154:157], v141
	ds_read_b128 v[158:161], v141 offset:1024
	ds_read_b128 v[162:165], v141 offset:2048
	ds_read_b128 v[166:169], v141 offset:3072
	s_add_i32 s74, s17, 0x80000
	s_mov_b32 m0, s48
	ds_read_b128 v[170:173], v140 offset:32768
	ds_read_b128 v[174:177], v140 offset:33792
	ds_read_b128 v[178:181], v140 offset:34816
	ds_read_b128 v[182:185], v140 offset:35840
	ds_read_b128 v[186:189], v140 offset:36864
	ds_read_b128 v[190:193], v140 offset:37888
	ds_read_b128 v[200:203], v140 offset:38912
	ds_read_b128 v[206:209], v140 offset:39936
	s_mov_b32 m0, s47
	s_nop 0
	buffer_load_dwordx4 v135, s[4:7], s17 offen lds
	s_mov_b32 m0, s48
	s_nop 0
	buffer_load_dwordx4 v0, s[4:7], s74 offen lds
	s_mov_b32 m0, s49
	s_nop 0
	buffer_load_dwordx4 v135, s[4:7], s74 offen lds
	s_waitcnt vmcnt(8)
	s_waitcnt lgkmcnt(0)
	s_barrier
	s_setprio 1
	s_waitcnt lgkmcnt(0)
	v_mfma_f32_16x16x32_bf16 v[126:129], v[130:133], v[170:173], v[126:129]
	v_mfma_f32_16x16x32_bf16 v[122:125], v[146:149], v[170:173], v[122:125]
	v_mfma_f32_16x16x32_bf16 v[106:109], v[146:149], v[178:181], v[106:109]
	v_mfma_f32_16x16x32_bf16 v[110:113], v[130:133], v[178:181], v[110:113]
	v_mfma_f32_16x16x32_bf16 v[94:97], v[130:133], v[186:189], v[94:97]
	v_mfma_f32_16x16x32_bf16 v[90:93], v[146:149], v[186:189], v[90:93]
	v_mfma_f32_16x16x32_bf16 v[74:77], v[146:149], v[200:203], v[74:77]
	v_mfma_f32_16x16x32_bf16 v[78:81], v[130:133], v[200:203], v[78:81]
	v_mfma_f32_16x16x32_bf16 v[126:129], v[142:145], v[174:177], v[126:129]
	v_mfma_f32_16x16x32_bf16 v[122:125], v[150:153], v[174:177], v[122:125]
	v_mfma_f32_16x16x32_bf16 v[106:109], v[150:153], v[182:185], v[106:109]
	v_mfma_f32_16x16x32_bf16 v[110:113], v[142:145], v[182:185], v[110:113]
	v_mfma_f32_16x16x32_bf16 v[94:97], v[142:145], v[190:193], v[94:97]
	v_mfma_f32_16x16x32_bf16 v[90:93], v[150:153], v[190:193], v[90:93]
	v_mfma_f32_16x16x32_bf16 v[74:77], v[150:153], v[206:209], v[74:77]
	v_mfma_f32_16x16x32_bf16 v[78:81], v[142:145], v[206:209], v[78:81]
	s_setprio 0
	s_setprio 1
	v_mfma_f32_16x16x32_bf16 v[118:121], v[154:157], v[170:173], v[118:121]
	v_mfma_f32_16x16x32_bf16 v[114:117], v[162:165], v[170:173], v[114:117]
	v_mfma_f32_16x16x32_bf16 v[98:101], v[162:165], v[178:181], v[98:101]
	v_mfma_f32_16x16x32_bf16 v[102:105], v[154:157], v[178:181], v[102:105]
	v_mfma_f32_16x16x32_bf16 v[86:89], v[154:157], v[186:189], v[86:89]
	v_mfma_f32_16x16x32_bf16 v[82:85], v[162:165], v[186:189], v[82:85]
	v_mfma_f32_16x16x32_bf16 v[66:69], v[162:165], v[200:203], v[66:69]
	v_mfma_f32_16x16x32_bf16 v[70:73], v[154:157], v[200:203], v[70:73]
	v_mfma_f32_16x16x32_bf16 v[118:121], v[158:161], v[174:177], v[118:121]
	v_mfma_f32_16x16x32_bf16 v[114:117], v[166:169], v[174:177], v[114:117]
	v_mfma_f32_16x16x32_bf16 v[98:101], v[166:169], v[182:185], v[98:101]
	v_mfma_f32_16x16x32_bf16 v[102:105], v[158:161], v[182:185], v[102:105]
	v_mfma_f32_16x16x32_bf16 v[86:89], v[158:161], v[190:193], v[86:89]
	v_mfma_f32_16x16x32_bf16 v[82:85], v[166:169], v[190:193], v[82:85]
	v_mfma_f32_16x16x32_bf16 v[66:69], v[166:169], v[206:209], v[66:69]
	v_mfma_f32_16x16x32_bf16 v[70:73], v[158:161], v[206:209], v[70:73]
	s_setprio 0
	s_barrier
	s_mov_b32 m0, s53
	s_add_i32 s74, s16, 0x80
	ds_read_b128 v[170:173], v140 offset:49152
	ds_read_b128 v[174:177], v140 offset:50176
	ds_read_b128 v[178:181], v140 offset:51200
	ds_read_b128 v[182:185], v140 offset:52224
	ds_read_b128 v[186:189], v140 offset:53248
	ds_read_b128 v[190:193], v140 offset:54272
	ds_read_b128 v[200:203], v140 offset:55296
	ds_read_b128 v[206:209], v140 offset:56320
	buffer_load_dwordx4 v134, s[40:43], s74 offen lds
	s_mov_b32 m0, s60
	s_add_i32 s16, s16, 0x80080
	buffer_load_dwordx4 v136, s[40:43], s74 offen lds
	s_mov_b32 m0, s63
	s_addk_i32 s17, 0x80
	buffer_load_dwordx4 v134, s[40:43], s16 offen lds
	s_mov_b32 m0, s66
	s_nop 0
	buffer_load_dwordx4 v136, s[40:43], s16 offen lds
	s_mov_b32 m0, s61
	s_nop 0
	buffer_load_dwordx4 v0, s[4:7], s17 offen lds
	s_waitcnt vmcnt(7)
	s_waitcnt lgkmcnt(0)
	s_barrier
	s_setprio 1
	s_waitcnt lgkmcnt(0)
	v_mfma_f32_16x16x32_bf16 v[62:65], v[130:133], v[170:173], v[62:65]
	v_mfma_f32_16x16x32_bf16 v[58:61], v[146:149], v[170:173], v[58:61]
	v_mfma_f32_16x16x32_bf16 v[42:45], v[146:149], v[178:181], v[42:45]
	v_mfma_f32_16x16x32_bf16 v[46:49], v[130:133], v[178:181], v[46:49]
	v_mfma_f32_16x16x32_bf16 v[30:33], v[130:133], v[186:189], v[30:33]
	v_mfma_f32_16x16x32_bf16 v[26:29], v[146:149], v[186:189], v[26:29]
	v_mfma_f32_16x16x32_bf16 v[10:13], v[146:149], v[200:203], v[10:13]
	v_mfma_f32_16x16x32_bf16 v[14:17], v[130:133], v[200:203], v[14:17]
	v_mfma_f32_16x16x32_bf16 v[62:65], v[142:145], v[174:177], v[62:65]
	v_mfma_f32_16x16x32_bf16 v[58:61], v[150:153], v[174:177], v[58:61]
	v_mfma_f32_16x16x32_bf16 v[42:45], v[150:153], v[182:185], v[42:45]
	v_mfma_f32_16x16x32_bf16 v[46:49], v[142:145], v[182:185], v[46:49]
	v_mfma_f32_16x16x32_bf16 v[30:33], v[142:145], v[190:193], v[30:33]
	v_mfma_f32_16x16x32_bf16 v[26:29], v[150:153], v[190:193], v[26:29]
	v_mfma_f32_16x16x32_bf16 v[10:13], v[150:153], v[206:209], v[10:13]
	v_mfma_f32_16x16x32_bf16 v[14:17], v[142:145], v[206:209], v[14:17]
	s_setprio 0
	s_setprio 1
	v_mfma_f32_16x16x32_bf16 v[54:57], v[154:157], v[170:173], v[54:57]
	v_mfma_f32_16x16x32_bf16 v[50:53], v[162:165], v[170:173], v[50:53]
	v_mfma_f32_16x16x32_bf16 v[34:37], v[162:165], v[178:181], v[34:37]
	v_mfma_f32_16x16x32_bf16 v[38:41], v[154:157], v[178:181], v[38:41]
	v_mfma_f32_16x16x32_bf16 v[22:25], v[154:157], v[186:189], v[22:25]
	v_mfma_f32_16x16x32_bf16 v[18:21], v[162:165], v[186:189], v[18:21]
	v_mfma_f32_16x16x32_bf16 v[2:5], v[162:165], v[200:203], v[2:5]
	v_mfma_f32_16x16x32_bf16 v[6:9], v[154:157], v[200:203], v[6:9]
	v_mfma_f32_16x16x32_bf16 v[54:57], v[158:161], v[174:177], v[54:57]
	v_mfma_f32_16x16x32_bf16 v[50:53], v[166:169], v[174:177], v[50:53]
	v_mfma_f32_16x16x32_bf16 v[34:37], v[166:169], v[182:185], v[34:37]
	v_mfma_f32_16x16x32_bf16 v[38:41], v[158:161], v[182:185], v[38:41]
	v_mfma_f32_16x16x32_bf16 v[22:25], v[158:161], v[190:193], v[22:25]
	v_mfma_f32_16x16x32_bf16 v[18:21], v[166:169], v[190:193], v[18:21]
	v_mfma_f32_16x16x32_bf16 v[2:5], v[166:169], v[206:209], v[2:5]
	v_mfma_f32_16x16x32_bf16 v[6:9], v[158:161], v[206:209], v[6:9]
	s_setprio 0
	s_barrier
	s_add_i32 s73, s73, 2
	s_add_u32 s19, s19, 0x100
	s_addc_u32 s21, s21, 0
	s_cmp_gt_u32 s73, 29
	s_mov_b64 s[16:17], s[38:39]
	s_cbranch_scc0 .LBB0_1514
	s_and_b64 vcc, exec, s[12:13]
	s_cbranch_vccz .LBB0_1517
	s_barrier

; #define PG8_STAGE(bufoff, gbase, voff) do { const int so_ = (int)(unsigned)((const char*)(gbase) - base_##voff); _Pragma("unroll") for (int _i = 0; _i < 2; ++_i) \
;         __builtin_amdgcn_raw_ptr_buffer_load_lds(rs_##voff, (PG8_LAS unsigned*)(lds + (bufoff) + ldsw + _i * 8192), 16, (int)(voff)[_i], so_, 0, 0); } while (0)
; #define PG8_LDA(dst, b, h) do { _Pragma("unroll") for (int m = 0; m < 4; ++m) _Pragma("unroll") for (int k = 0; k < 2; ++k) dst[m][k] = *(const PG8_LAS bf16x8*)(lds + PG8_SA(b, h) + aoff + m * 2048 + k * 1024); } while (0)
; #define PG8_LDB(dst, b, h) do { _Pragma("unroll") for (int n = 0; n < 2; ++n) _Pragma("unroll") for (int k = 0; k < 2; ++k) dst[n][k] = *(const PG8_LAS bf16x8*)(lds + PG8_SB(b, h) + boff + n * 2048 + k * 1024); } while (0)
; #define PG8_MMA(ai, bj, At, Bt) do { __builtin_amdgcn_s_setprio(1); _Pragma("unroll") for (int m = 0; m < 4; ++m) _Pragma("unroll") for (int n = 0; n < 2; ++n) _Pragma("unroll") for (int k = 0; k < 2; ++k) \
;         acc[ai][bj][m][n] = __builtin_amdgcn_mfma_f32_16x16x32_bf16(Bt[n][k], At[m][k], acc[ai][bj][m][n], 0, 0, 0); __builtin_amdgcn_s_setprio(0); } while (0)
; #define PG8_WAIT_V(n) asm volatile("s_waitcnt vmcnt(" #n ")" ::: "memory")
; #define PG8_WAIT_L(n) asm volatile("s_waitcnt lgkmcnt(" #n ")" ::: "memory")
; #define PG8_BAR __builtin_amdgcn_s_barrier()
; #define PG8_SCHED __builtin_amdgcn_sched_barrier(0)
; template <class Epi, class Sched, bool ALIGN_EPI = false, bool SP2 = false>
; __device__ __forceinline__ void gemm_phase(PG8_LAS unsigned char* lds, const Gemm g, const Sched& S, const Epi& E, int tid_in) {
;     ...
;             PG8_LDB(B0, 0, 0); PG8_LDB(B1, 0, 1); PG8_SCHED; PG8_LDA(At, 0, 0); PG8_STAGE(PG8_SA(1, 1), a1 + hstepA, voffA);
;             PG8_WAIT_V(8); PG8_WAIT_L(0); PG8_BAR; PG8_MMA(0, 0, At, B0); PG8_MMA(0, 1, At, B1); PG8_BAR; PG8_SCHED;
;             PG8_LDA(At, 0, 1); PG8_STAGE(PG8_SB(0, 0), b2, voffB); PG8_STAGE(PG8_SB(0, 1), b2 + hstepB, voffB); PG8_STAGE(PG8_SA(0, 0), a2, voffA);
;             PG8_WAIT_V(8); PG8_WAIT_L(0); PG8_BAR; PG8_MMA(1, 0, At, B0); PG8_MMA(1, 1, At, B1); PG8_BAR; PG8_SCHED;
.LBB0_1584:
	v_add_u32_e32 v133, 0x10000, v131
	ds_read_b128 v[134:137], v133
	ds_read_b128 v[138:141], v133 offset:1024
	ds_read_b128 v[142:145], v133 offset:2048
	ds_read_b128 v[146:149], v133 offset:3072
	v_add_u32_e32 v133, 0x14000, v131
	ds_read_b128 v[150:153], v133
	ds_read_b128 v[154:157], v133 offset:1024
	ds_read_b128 v[158:161], v133 offset:2048
	ds_read_b128 v[166:169], v133 offset:3072
	s_add_i32 s43, s38, s22
	s_add_i32 s42, s14, s22
	s_add_i32 s76, s12, s22
	s_addk_i32 s43, 0xff80
	s_sub_i32 s78, s43, 0x160000
	s_cmpk_eq_i32 s39, 0x54
	s_cselect_b32 s77, s16, s42
	s_mov_b32 m0, s68
	ds_read_b128 v[170:173], v132
	ds_read_b128 v[174:177], v132 offset:1024
	ds_read_b128 v[178:181], v132 offset:2048
	ds_read_b128 v[182:185], v132 offset:3072
	ds_read_b128 v[186:189], v132 offset:4096
	ds_read_b128 v[190:193], v132 offset:5120
	ds_read_b128 v[200:203], v132 offset:6144
	ds_read_b128 v[206:209], v132 offset:7168
	s_mov_b32 m0, s63
	s_nop 0
	buffer_load_dwordx4 v130, s[4:7], s78 offen lds
	s_mov_b32 m0, s68
	s_nop 0
	buffer_load_dwordx4 v0, s[4:7], s43 offen lds
	s_mov_b32 m0, s69
	s_nop 0
	buffer_load_dwordx4 v130, s[4:7], s43 offen lds
	s_waitcnt vmcnt(8)
	s_waitcnt lgkmcnt(0)
	s_barrier
	s_setprio 1
	s_waitcnt lgkmcnt(0)
	v_mfma_f32_16x16x32_bf16 v[22:25], v[134:137], v[170:173], v[22:25]
	v_mfma_f32_16x16x32_bf16 v[14:17], v[142:145], v[170:173], v[14:17]
	v_mfma_f32_16x16x32_bf16 v[54:57], v[142:145], v[178:181], v[54:57]
	v_mfma_f32_16x16x32_bf16 v[74:77], v[134:137], v[178:181], v[74:77]
	v_mfma_f32_16x16x32_bf16 v[106:109], v[134:137], v[186:189], v[106:109]
	v_mfma_f32_16x16x32_bf16 v[102:105], v[142:145], v[186:189], v[102:105]
	v_mfma_f32_16x16x32_bf16 v[118:121], v[142:145], v[200:203], v[118:121]
	v_mfma_f32_16x16x32_bf16 v[122:125], v[134:137], v[200:203], v[122:125]
	v_mfma_f32_16x16x32_bf16 v[22:25], v[138:141], v[174:177], v[22:25]
	v_mfma_f32_16x16x32_bf16 v[14:17], v[146:149], v[174:177], v[14:17]
	v_mfma_f32_16x16x32_bf16 v[54:57], v[146:149], v[182:185], v[54:57]
	v_mfma_f32_16x16x32_bf16 v[74:77], v[138:141], v[182:185], v[74:77]
	v_mfma_f32_16x16x32_bf16 v[106:109], v[138:141], v[190:193], v[106:109]
	v_mfma_f32_16x16x32_bf16 v[102:105], v[146:149], v[190:193], v[102:105]
	v_mfma_f32_16x16x32_bf16 v[118:121], v[146:149], v[206:209], v[118:121]
	v_mfma_f32_16x16x32_bf16 v[122:125], v[138:141], v[206:209], v[122:125]
	s_setprio 0
	s_setprio 1
	v_mfma_f32_16x16x32_bf16 v[6:9], v[150:153], v[170:173], v[6:9]
	v_mfma_f32_16x16x32_bf16 v[18:21], v[158:161], v[170:173], v[18:21]
	v_mfma_f32_16x16x32_bf16 v[78:81], v[158:161], v[178:181], v[78:81]
	v_mfma_f32_16x16x32_bf16 v[50:53], v[150:153], v[178:181], v[50:53]
	v_mfma_f32_16x16x32_bf16 v[98:101], v[150:153], v[186:189], v[98:101]
	v_mfma_f32_16x16x32_bf16 v[110:113], v[158:161], v[186:189], v[110:113]
	v_mfma_f32_16x16x32_bf16 v[126:129], v[158:161], v[200:203], v[126:129]
	v_mfma_f32_16x16x32_bf16 v[114:117], v[150:153], v[200:203], v[114:117]
	v_mfma_f32_16x16x32_bf16 v[6:9], v[154:157], v[174:177], v[6:9]
	v_mfma_f32_16x16x32_bf16 v[18:21], v[166:169], v[174:177], v[18:21]
	v_mfma_f32_16x16x32_bf16 v[78:81], v[166:169], v[182:185], v[78:81]
	v_mfma_f32_16x16x32_bf16 v[50:53], v[154:157], v[182:185], v[50:53]
	v_mfma_f32_16x16x32_bf16 v[98:101], v[154:157], v[190:193], v[98:101]
	v_mfma_f32_16x16x32_bf16 v[110:113], v[166:169], v[190:193], v[110:113]
	v_mfma_f32_16x16x32_bf16 v[126:129], v[166:169], v[206:209], v[126:129]
	v_mfma_f32_16x16x32_bf16 v[114:117], v[154:157], v[206:209], v[114:117]
	s_setprio 0
	s_barrier
	s_cselect_b32 s76, s20, s76
	s_mov_b32 m0, s26
	s_mov_b32 s42, s6
	s_mov_b32 s43, s7
	s_sub_i32 s76, s76, s40
	ds_read_b128 v[170:173], v132 offset:16384
	ds_read_b128 v[174:177], v132 offset:17408
	ds_read_b128 v[178:181], v132 offset:18432
	ds_read_b128 v[182:185], v132 offset:19456
	ds_read_b128 v[186:189], v132 offset:20480
	ds_read_b128 v[190:193], v132 offset:21504
	ds_read_b128 v[200:203], v132 offset:22528
	ds_read_b128 v[206:209], v132 offset:23552
	buffer_load_dwordx4 v0, s[40:43], s76 offen lds
	s_mov_b32 m0, s44
	s_add_i32 s78, s76, 0x160000
	buffer_load_dwordx4 v130, s[40:43], s76 offen lds
	s_mov_b32 m0, s45
	s_sub_i32 s77, s77, s4
	buffer_load_dwordx4 v0, s[40:43], s78 offen lds
	s_mov_b32 m0, s46
	s_nop 0
	buffer_load_dwordx4 v130, s[40:43], s78 offen lds
	s_mov_b32 m0, s19
	s_nop 0
	buffer_load_dwordx4 v0, s[4:7], s77 offen lds
	s_waitcnt vmcnt(7)
	s_waitcnt lgkmcnt(0)
	s_barrier
	s_setprio 1
	s_waitcnt lgkmcnt(0)
	v_mfma_f32_16x16x32_bf16 v[62:65], v[134:137], v[170:173], v[62:65]
	v_mfma_f32_16x16x32_bf16 v[46:49], v[142:145], v[170:173], v[46:49]
	v_mfma_f32_16x16x32_bf16 v[70:73], v[142:145], v[178:181], v[70:73]
	v_mfma_f32_16x16x32_bf16 v[82:85], v[134:137], v[178:181], v[82:85]
	v_mfma_f32_16x16x32_bf16 v[94:97], v[134:137], v[186:189], v[94:97]
	v_mfma_f32_16x16x32_bf16 v[90:93], v[142:145], v[186:189], v[90:93]
	v_mfma_f32_16x16x32_bf16 v[26:29], v[142:145], v[200:203], v[26:29]
	v_mfma_f32_16x16x32_bf16 v[38:41], v[134:137], v[200:203], v[38:41]
	v_mfma_f32_16x16x32_bf16 v[62:65], v[138:141], v[174:177], v[62:65]
	v_mfma_f32_16x16x32_bf16 v[46:49], v[146:149], v[174:177], v[46:49]
	v_mfma_f32_16x16x32_bf16 v[70:73], v[146:149], v[182:185], v[70:73]
	v_mfma_f32_16x16x32_bf16 v[82:85], v[138:141], v[182:185], v[82:85]
	v_mfma_f32_16x16x32_bf16 v[94:97], v[138:141], v[190:193], v[94:97]
	v_mfma_f32_16x16x32_bf16 v[90:93], v[146:149], v[190:193], v[90:93]
	v_mfma_f32_16x16x32_bf16 v[26:29], v[146:149], v[206:209], v[26:29]
	v_mfma_f32_16x16x32_bf16 v[38:41], v[138:141], v[206:209], v[38:41]
	s_setprio 0
	s_setprio 1
	v_mfma_f32_16x16x32_bf16 v[42:45], v[150:153], v[170:173], v[42:45]
	v_mfma_f32_16x16x32_bf16 v[30:33], v[158:161], v[170:173], v[30:33]
	v_mfma_f32_16x16x32_bf16 v[86:89], v[158:161], v[178:181], v[86:89]
	v_mfma_f32_16x16x32_bf16 v[66:69], v[150:153], v[178:181], v[66:69]
	v_mfma_f32_16x16x32_bf16 v[58:61], v[150:153], v[186:189], v[58:61]
	v_mfma_f32_16x16x32_bf16 v[34:37], v[158:161], v[186:189], v[34:37]
	v_mfma_f32_16x16x32_bf16 v[2:5], v[158:161], v[200:203], v[2:5]
	v_mfma_f32_16x16x32_bf16 v[10:13], v[150:153], v[200:203], v[10:13]
	v_mfma_f32_16x16x32_bf16 v[42:45], v[154:157], v[174:177], v[42:45]
	v_mfma_f32_16x16x32_bf16 v[30:33], v[166:169], v[174:177], v[30:33]
	v_mfma_f32_16x16x32_bf16 v[86:89], v[166:169], v[182:185], v[86:89]
	v_mfma_f32_16x16x32_bf16 v[66:69], v[154:157], v[182:185], v[66:69]
	v_mfma_f32_16x16x32_bf16 v[58:61], v[154:157], v[190:193], v[58:61]
	v_mfma_f32_16x16x32_bf16 v[34:37], v[166:169], v[190:193], v[34:37]
	v_mfma_f32_16x16x32_bf16 v[2:5], v[166:169], v[206:209], v[2:5]
	v_mfma_f32_16x16x32_bf16 v[10:13], v[154:157], v[206:209], v[10:13]
	s_setprio 0
	s_barrier
; #define PG8_STAGE(bufoff, gbase, voff) do { const int so_ = (int)(unsigned)((const char*)(gbase) - base_##voff); _Pragma("unroll") for (int _i = 0; _i < 2; ++_i) \
;         __builtin_amdgcn_raw_ptr_buffer_load_lds(rs_##voff, (PG8_LAS unsigned*)(lds + (bufoff) + ldsw + _i * 8192), 16, (int)(voff)[_i], so_, 0, 0); } while (0)
; #define PG8_LDA(dst, b, h) do { _Pragma("unroll") for (int m = 0; m < 4; ++m) _Pragma("unroll") for (int k = 0; k < 2; ++k) dst[m][k] = *(const PG8_LAS bf16x8*)(lds + PG8_SA(b, h) + aoff + m * 2048 + k * 1024); } while (0)
; #define PG8_LDB(dst, b, h) do { _Pragma("unroll") for (int n = 0; n < 2; ++n) _Pragma("unroll") for (int k = 0; k < 2; ++k) dst[n][k] = *(const PG8_LAS bf16x8*)(lds + PG8_SB(b, h) + boff + n * 2048 + k * 1024); } while (0)
; #define PG8_MMA(ai, bj, At, Bt) do { __builtin_amdgcn_s_setprio(1); _Pragma("unroll") for (int m = 0; m < 4; ++m) _Pragma("unroll") for (int n = 0; n < 2; ++n) _Pragma("unroll") for (int k = 0; k < 2; ++k) \
;         acc[ai][bj][m][n] = __builtin_amdgcn_mfma_f32_16x16x32_bf16(Bt[n][k], At[m][k], acc[ai][bj][m][n], 0, 0, 0); __builtin_amdgcn_s_setprio(0); } while (0)
; #define PG8_WAIT_V(n) asm volatile("s_waitcnt vmcnt(" #n ")" ::: "memory")
; #define PG8_WAIT_L(n) asm volatile("s_waitcnt lgkmcnt(" #n ")" ::: "memory")
; #define PG8_BAR __builtin_amdgcn_s_barrier()
; #define PG8_SCHED __builtin_amdgcn_sched_barrier(0)
; template <class Epi, class Sched, bool ALIGN_EPI = false, bool SP2 = false>
; __device__ __forceinline__ void gemm_phase(PG8_LAS unsigned char* lds, const Gemm g, const Sched& S, const Epi& E, int tid_in) {
;     ...
;             PG8_LDB(B0, 1, 0); PG8_LDB(B1, 1, 1); PG8_SCHED; PG8_LDA(At, 1, 0); PG8_STAGE(PG8_SA(0, 1), a2 + hstepA, voffA);
;             PG8_WAIT_V(8); PG8_WAIT_L(0); PG8_BAR; PG8_MMA(0, 0, At, B0); PG8_MMA(0, 1, At, B1); PG8_BAR; PG8_SCHED;
;             PG8_LDA(At, 1, 1); PG8_STAGE(PG8_SB(1, 0), b3, voffB); PG8_STAGE(PG8_SB(1, 1), b3 + hstepB, voffB); PG8_STAGE(PG8_SA(1, 0), a3, voffA);
	v_add_u32_e32 v133, 0x18000, v131
	ds_read_b128 v[134:137], v133
	ds_read_b128 v[138:141], v133 offset:1024
	ds_read_b128 v[142:145], v133 offset:2048
	ds_read_b128 v[146:149], v133 offset:3072
	v_add_u32_e32 v133, 0x1c000, v131
	ds_read_b128 v[150:153], v133
	ds_read_b128 v[154:157], v133 offset:1024
	ds_read_b128 v[158:161], v133 offset:2048
	ds_read_b128 v[166:169], v133 offset:3072
	s_add_i32 s78, s77, 0x160000
	s_mov_b32 m0, s48
	ds_read_b128 v[170:173], v132 offset:32768
	ds_read_b128 v[174:177], v132 offset:33792
	ds_read_b128 v[178:181], v132 offset:34816
	ds_read_b128 v[182:185], v132 offset:35840
	ds_read_b128 v[186:189], v132 offset:36864
	ds_read_b128 v[190:193], v132 offset:37888
	ds_read_b128 v[200:203], v132 offset:38912
	ds_read_b128 v[206:209], v132 offset:39936
	s_mov_b32 m0, s47
	s_nop 0
	buffer_load_dwordx4 v130, s[4:7], s77 offen lds
	s_mov_b32 m0, s48
	s_nop 0
	buffer_load_dwordx4 v0, s[4:7], s78 offen lds
	s_mov_b32 m0, s49
	s_nop 0
	buffer_load_dwordx4 v130, s[4:7], s78 offen lds
	s_waitcnt vmcnt(8)
	s_waitcnt lgkmcnt(0)
	s_barrier
	s_setprio 1
	s_waitcnt lgkmcnt(0)
	v_mfma_f32_16x16x32_bf16 v[22:25], v[134:137], v[170:173], v[22:25]
	v_mfma_f32_16x16x32_bf16 v[14:17], v[142:145], v[170:173], v[14:17]
	v_mfma_f32_16x16x32_bf16 v[54:57], v[142:145], v[178:181], v[54:57]
	v_mfma_f32_16x16x32_bf16 v[74:77], v[134:137], v[178:181], v[74:77]
	v_mfma_f32_16x16x32_bf16 v[106:109], v[134:137], v[186:189], v[106:109]
	v_mfma_f32_16x16x32_bf16 v[102:105], v[142:145], v[186:189], v[102:105]
	v_mfma_f32_16x16x32_bf16 v[118:121], v[142:145], v[200:203], v[118:121]
	v_mfma_f32_16x16x32_bf16 v[122:125], v[134:137], v[200:203], v[122:125]
	v_mfma_f32_16x16x32_bf16 v[22:25], v[138:141], v[174:177], v[22:25]
	v_mfma_f32_16x16x32_bf16 v[14:17], v[146:149], v[174:177], v[14:17]
	v_mfma_f32_16x16x32_bf16 v[54:57], v[146:149], v[182:185], v[54:57]
	v_mfma_f32_16x16x32_bf16 v[74:77], v[138:141], v[182:185], v[74:77]
	v_mfma_f32_16x16x32_bf16 v[106:109], v[138:141], v[190:193], v[106:109]
	v_mfma_f32_16x16x32_bf16 v[102:105], v[146:149], v[190:193], v[102:105]
	v_mfma_f32_16x16x32_bf16 v[118:121], v[146:149], v[206:209], v[118:121]
	v_mfma_f32_16x16x32_bf16 v[122:125], v[138:141], v[206:209], v[122:125]
	s_setprio 0
	s_setprio 1
	v_mfma_f32_16x16x32_bf16 v[6:9], v[150:153], v[170:173], v[6:9]
	v_mfma_f32_16x16x32_bf16 v[18:21], v[158:161], v[170:173], v[18:21]
	v_mfma_f32_16x16x32_bf16 v[78:81], v[158:161], v[178:181], v[78:81]
	v_mfma_f32_16x16x32_bf16 v[50:53], v[150:153], v[178:181], v[50:53]
	v_mfma_f32_16x16x32_bf16 v[98:101], v[150:153], v[186:189], v[98:101]
	v_mfma_f32_16x16x32_bf16 v[110:113], v[158:161], v[186:189], v[110:113]
	v_mfma_f32_16x16x32_bf16 v[126:129], v[158:161], v[200:203], v[126:129]
	v_mfma_f32_16x16x32_bf16 v[114:117], v[150:153], v[200:203], v[114:117]
	v_mfma_f32_16x16x32_bf16 v[6:9], v[154:157], v[174:177], v[6:9]
	v_mfma_f32_16x16x32_bf16 v[18:21], v[166:169], v[174:177], v[18:21]
	v_mfma_f32_16x16x32_bf16 v[78:81], v[166:169], v[182:185], v[78:81]
	v_mfma_f32_16x16x32_bf16 v[50:53], v[154:157], v[182:185], v[50:53]
	v_mfma_f32_16x16x32_bf16 v[98:101], v[154:157], v[190:193], v[98:101]
	v_mfma_f32_16x16x32_bf16 v[110:113], v[166:169], v[190:193], v[110:113]
	v_mfma_f32_16x16x32_bf16 v[126:129], v[166:169], v[206:209], v[126:129]
	v_mfma_f32_16x16x32_bf16 v[114:117], v[154:157], v[206:209], v[114:117]
	s_setprio 0
	s_barrier
	s_mov_b32 m0, s60
	s_add_i32 s78, s76, 0x80
	ds_read_b128 v[170:173], v132 offset:49152
	ds_read_b128 v[174:177], v132 offset:50176
	ds_read_b128 v[178:181], v132 offset:51200
	ds_read_b128 v[182:185], v132 offset:52224
	ds_read_b128 v[186:189], v132 offset:53248
	ds_read_b128 v[190:193], v132 offset:54272
	ds_read_b128 v[200:203], v132 offset:55296
	ds_read_b128 v[206:209], v132 offset:56320
	buffer_load_dwordx4 v0, s[40:43], s78 offen lds
	s_mov_b32 m0, s61
	s_add_i32 s76, s76, 0x160080
	buffer_load_dwordx4 v130, s[40:43], s78 offen lds
	s_mov_b32 m0, s66
	s_addk_i32 s77, 0x80
	buffer_load_dwordx4 v0, s[40:43], s76 offen lds
	s_mov_b32 m0, s67
	s_nop 0
	buffer_load_dwordx4 v130, s[40:43], s76 offen lds
	s_mov_b32 m0, s62
	s_nop 0
	buffer_load_dwordx4 v0, s[4:7], s77 offen lds
	s_waitcnt vmcnt(7)
	s_waitcnt lgkmcnt(0)
	s_barrier
; #define PG8_MMA(ai, bj, At, Bt) do { __builtin_amdgcn_s_setprio(1); _Pragma("unroll") for (int m = 0; m < 4; ++m) _Pragma("unroll") for (int n = 0; n < 2; ++n) _Pragma("unroll") for (int k = 0; k < 2; ++k) \
;         acc[ai][bj][m][n] = __builtin_amdgcn_mfma_f32_16x16x32_bf16(Bt[n][k], At[m][k], acc[ai][bj][m][n], 0, 0, 0); __builtin_amdgcn_s_setprio(0); } while (0)
; #define PG8_WAIT_V(n) asm volatile("s_waitcnt vmcnt(" #n ")" ::: "memory")
; #define PG8_WAIT_L(n) asm volatile("s_waitcnt lgkmcnt(" #n ")" ::: "memory")
; #define PG8_BAR __builtin_amdgcn_s_barrier()
; #define PG8_SCHED __builtin_amdgcn_sched_barrier(0)
; template <class Epi, class Sched, bool ALIGN_EPI = false, bool SP2 = false>
; __device__ __forceinline__ void gemm_phase(PG8_LAS unsigned char* lds, const Gemm g, const Sched& S, const Epi& E, int tid_in) {
;     ...
;             PG8_WAIT_V(8); PG8_WAIT_L(0); PG8_BAR; PG8_MMA(1, 0, At, B0); PG8_MMA(1, 1, At, B1); PG8_BAR; PG8_SCHED;
;     ...
;         if (zero_acc) {
; #pragma unroll
;         for (int a = 0; a < 2; ++a)
; #pragma unroll
;             for (int b = 0; b < 2; ++b)
; #pragma unroll
;                 for (int m = 0; m < 4; ++m)
; #pragma unroll
;                     for (int n = 0; n < 2; ++n) acc[a][b][m][n] = (f32x4){0.f, 0.f, 0.f, 0.f};
;         }
;         cur = nxt; cA = nA; cB = nB; ++ui;
	s_setprio 1
	s_waitcnt lgkmcnt(0)
	v_mfma_f32_16x16x32_bf16 v[62:65], v[134:137], v[170:173], v[62:65]
	v_mfma_f32_16x16x32_bf16 v[46:49], v[142:145], v[170:173], v[46:49]
	v_mfma_f32_16x16x32_bf16 v[70:73], v[142:145], v[178:181], v[70:73]
	v_mfma_f32_16x16x32_bf16 v[82:85], v[134:137], v[178:181], v[82:85]
	v_mfma_f32_16x16x32_bf16 v[94:97], v[134:137], v[186:189], v[94:97]
	v_mfma_f32_16x16x32_bf16 v[90:93], v[142:145], v[186:189], v[90:93]
	v_mfma_f32_16x16x32_bf16 v[26:29], v[142:145], v[200:203], v[26:29]
	v_mfma_f32_16x16x32_bf16 v[38:41], v[134:137], v[200:203], v[38:41]
	v_mfma_f32_16x16x32_bf16 v[62:65], v[138:141], v[174:177], v[62:65]
	v_mfma_f32_16x16x32_bf16 v[46:49], v[146:149], v[174:177], v[46:49]
	v_mfma_f32_16x16x32_bf16 v[70:73], v[146:149], v[182:185], v[70:73]
	v_mfma_f32_16x16x32_bf16 v[82:85], v[138:141], v[182:185], v[82:85]
	v_mfma_f32_16x16x32_bf16 v[94:97], v[138:141], v[190:193], v[94:97]
	v_mfma_f32_16x16x32_bf16 v[90:93], v[146:149], v[190:193], v[90:93]
	v_mfma_f32_16x16x32_bf16 v[26:29], v[146:149], v[206:209], v[26:29]
	v_mfma_f32_16x16x32_bf16 v[38:41], v[138:141], v[206:209], v[38:41]
	s_setprio 0
	s_setprio 1
	v_mfma_f32_16x16x32_bf16 v[42:45], v[150:153], v[170:173], v[42:45]
	v_mfma_f32_16x16x32_bf16 v[30:33], v[158:161], v[170:173], v[30:33]
	v_mfma_f32_16x16x32_bf16 v[86:89], v[158:161], v[178:181], v[86:89]
	v_mfma_f32_16x16x32_bf16 v[66:69], v[150:153], v[178:181], v[66:69]
	v_mfma_f32_16x16x32_bf16 v[58:61], v[150:153], v[186:189], v[58:61]
	v_mfma_f32_16x16x32_bf16 v[34:37], v[158:161], v[186:189], v[34:37]
	v_mfma_f32_16x16x32_bf16 v[2:5], v[158:161], v[200:203], v[2:5]
	v_mfma_f32_16x16x32_bf16 v[10:13], v[150:153], v[200:203], v[10:13]
	v_mfma_f32_16x16x32_bf16 v[42:45], v[154:157], v[174:177], v[42:45]
	v_mfma_f32_16x16x32_bf16 v[30:33], v[166:169], v[174:177], v[30:33]
	v_mfma_f32_16x16x32_bf16 v[86:89], v[166:169], v[182:185], v[86:89]
	v_mfma_f32_16x16x32_bf16 v[66:69], v[154:157], v[182:185], v[66:69]
	v_mfma_f32_16x16x32_bf16 v[58:61], v[154:157], v[190:193], v[58:61]
	v_mfma_f32_16x16x32_bf16 v[34:37], v[166:169], v[190:193], v[34:37]
	v_mfma_f32_16x16x32_bf16 v[2:5], v[166:169], v[206:209], v[2:5]
	v_mfma_f32_16x16x32_bf16 v[10:13], v[154:157], v[206:209], v[10:13]
	s_setprio 0
	s_barrier
	s_add_i32 s39, s39, 2
	s_add_u32 s22, s22, 0x100
	s_addc_u32 s23, s23, 0
	s_cmpk_gt_u32 s39, 0x55
	s_cbranch_scc0 .LBB0_1584
	s_and_b64 vcc, exec, s[36:37]
	s_cbranch_vccnz .LBB0_1572
	v_mov_b32_e32 v2, 0
	s_mov_b32 s10, s73
	s_mov_b32 s25, s74
	s_mov_b64 s[12:13], s[20:21]
	s_mov_b64 s[14:15], s[16:17]
	s_mov_b32 s72, s75
	v_mov_b32_e32 v3, v2
	v_mov_b32_e32 v4, v2
	v_mov_b32_e32 v5, v2
	v_mov_b32_e32 v10, v2
	v_mov_b32_e32 v11, v2
	v_mov_b32_e32 v12, v2
	v_mov_b32_e32 v13, v2
	v_mov_b32_e32 v34, v2
	v_mov_b32_e32 v35, v2
	v_mov_b32_e32 v36, v2
	v_mov_b32_e32 v37, v2
	v_mov_b32_e32 v58, v2
	v_mov_b32_e32 v59, v2
	v_mov_b32_e32 v60, v2
	v_mov_b32_e32 v61, v2
	v_mov_b32_e32 v86, v2
	v_mov_b32_e32 v87, v2
	v_mov_b32_e32 v88, v2
	v_mov_b32_e32 v89, v2
	v_mov_b32_e32 v66, v2
	v_mov_b32_e32 v67, v2
	v_mov_b32_e32 v68, v2
	v_mov_b32_e32 v69, v2
	v_mov_b32_e32 v30, v2
	v_mov_b32_e32 v31, v2
	v_mov_b32_e32 v32, v2
	v_mov_b32_e32 v33, v2
	v_mov_b32_e32 v42, v2
	v_mov_b32_e32 v43, v2
	v_mov_b32_e32 v44, v2
	v_mov_b32_e32 v45, v2
	v_mov_b32_e32 v26, v2
	v_mov_b32_e32 v27, v2
	v_mov_b32_e32 v28, v2
	v_mov_b32_e32 v29, v2
	v_mov_b32_e32 v38, v2
	v_mov_b32_e32 v39, v2
	v_mov_b32_e32 v40, v2
	v_mov_b32_e32 v41, v2
	v_mov_b32_e32 v90, v2
	v_mov_b32_e32 v91, v2
	v_mov_b32_e32 v92, v2
	v_mov_b32_e32 v93, v2
	v_mov_b32_e32 v94, v2
	v_mov_b32_e32 v95, v2
	v_mov_b32_e32 v96, v2
	v_mov_b32_e32 v97, v2
	v_mov_b32_e32 v70, v2
	v_mov_b32_e32 v71, v2
	v_mov_b32_e32 v72, v2
	v_mov_b32_e32 v73, v2
	v_mov_b32_e32 v82, v2
	v_mov_b32_e32 v83, v2
	v_mov_b32_e32 v84, v2
	v_mov_b32_e32 v85, v2
	v_mov_b32_e32 v46, v2
	v_mov_b32_e32 v47, v2
	v_mov_b32_e32 v48, v2
	v_mov_b32_e32 v49, v2
	v_mov_b32_e32 v62, v2
	v_mov_b32_e32 v63, v2
	v_mov_b32_e32 v64, v2
	v_mov_b32_e32 v65, v2
	v_mov_b32_e32 v126, v2
	v_mov_b32_e32 v127, v2
	v_mov_b32_e32 v128, v2
	v_mov_b32_e32 v129, v2
	v_mov_b32_e32 v114, v2
	v_mov_b32_e32 v115, v2
	v_mov_b32_e32 v116, v2
	v_mov_b32_e32 v117, v2
	v_mov_b32_e32 v110, v2
	v_mov_b32_e32 v111, v2
	v_mov_b32_e32 v112, v2
	v_mov_b32_e32 v113, v2
	v_mov_b32_e32 v98, v2
	v_mov_b32_e32 v99, v2
	v_mov_b32_e32 v100, v2
	v_mov_b32_e32 v101, v2
	v_mov_b32_e32 v78, v2
	v_mov_b32_e32 v79, v2
	v_mov_b32_e32 v80, v2
	v_mov_b32_e32 v81, v2
	v_mov_b32_e32 v50, v2
	v_mov_b32_e32 v51, v2
	v_mov_b32_e32 v52, v2
	v_mov_b32_e32 v53, v2
	v_mov_b32_e32 v18, v2
	v_mov_b32_e32 v19, v2
	v_mov_b32_e32 v20, v2
	v_mov_b32_e32 v21, v2
	v_mov_b32_e32 v6, v2
	v_mov_b32_e32 v7, v2
	v_mov_b32_e32 v8, v2
	v_mov_b32_e32 v9, v2
	v_mov_b32_e32 v118, v2
	v_mov_b32_e32 v119, v2
	v_mov_b32_e32 v120, v2
	v_mov_b32_e32 v121, v2
	v_mov_b32_e32 v122, v2
	v_mov_b32_e32 v123, v2
	v_mov_b32_e32 v124, v2
	v_mov_b32_e32 v125, v2
	v_mov_b32_e32 v102, v2
	v_mov_b32_e32 v103, v2
	v_mov_b32_e32 v104, v2
	v_mov_b32_e32 v105, v2
	v_mov_b32_e32 v106, v2
	v_mov_b32_e32 v107, v2
	v_mov_b32_e32 v108, v2
	v_mov_b32_e32 v109, v2
	v_mov_b32_e32 v54, v2
	v_mov_b32_e32 v55, v2
	v_mov_b32_e32 v56, v2
	v_mov_b32_e32 v57, v2
	v_mov_b32_e32 v74, v2
	v_mov_b32_e32 v75, v2
	v_mov_b32_e32 v76, v2
	v_mov_b32_e32 v77, v2
	v_mov_b32_e32 v14, v2
	v_mov_b32_e32 v15, v2
	v_mov_b32_e32 v16, v2
	v_mov_b32_e32 v17, v2
	v_mov_b32_e32 v22, v2
	v_mov_b32_e32 v23, v2
	v_mov_b32_e32 v24, v2
	v_mov_b32_e32 v25, v2
	s_branch .LBB0_1572
